# attention loop software-pipelined inside each wave at half-tile granularity (softmax VALU in MFMA gaps, all waves same code, one barrier per tile, 2-tile global prefetch, no C block)
# baseline (speedup 1.0000x reference)
; __device__ __forceinline__ int swap23(int p) { return (p & ~12) | ((p & 4) << 1) | ((p & 8) >> 1); }
; #define A_STORE(buf) do { LAS unsigned char* bb = lds + (buf) * ABUF; \
;         *(LAS u32x4*)(bb + kr1 * KT_PITCH + kc1 * 16) = st[0]; *(LAS u32x4*)(bb + kr2 * KT_PITCH + kc2 * 16) = st[1]; *(LAS u32x4*)(bb + kr3 * KT_PITCH + kc3 * 16) = st[2]; \
;         *(LAS u32x4*)(bb + KT_BYTES + vd1 * VT_PITCH + vc * 16) = st[3]; *(LAS u32x4*)(bb + KT_BYTES + vd2 * VT_PITCH + vc * 16) = st[4]; } while (0)
; __device__ __forceinline__ void attn_unit(KParams& P, int l, const AUnit& U, LAS unsigned char* lds) {
;     ...
;     const bool valid = i < U.nq; const int row = U.qrow0 + (valid ? i : 0);
;     bf16x8 qf[10];
;     { const bf16_t* qr = Qb + (size_t)row * NQ;
; #pragma unroll
;       for (int s = 0; s < 8; ++s) qf[s] = *(const bf16x8*)(qr + h * 128 + 16 * s + 8 * hi);
; #pragma unroll
;       for (int s = 0; s < 2; ++s) qf[8 + s] = *(const bf16x8*)(qr + 1024 + h * 32 + 16 * s + 8 * hi);
;       if (!valid) {
; #pragma unroll
;           for (int s = 0; s < 10; ++s) qf[s] = (bf16x8){0, 0, 0, 0, 0, 0, 0, 0}; } }
;     u32x4 st[5];
;     const int kr1 = tid / 20, kc1 = tid % 20, kr2 = (tid + 512) / 20, kc2 = (tid + 512) % 20, kr3 = ((tid & 255) + 1024) / 20, kc3 = ((tid & 255) + 1024) % 20;
;     const int vd1 = tid >> 3, vc = tid & 7, vd2 = vd1 + 64;
;     ...
;     A_LOAD(0); A_STORE(0);
;     __syncthreads();
;     f32x16 o[4];
; #pragma unroll
;     for (int d = 0; d < 4; ++d)
; #pragma unroll
;         for (int r = 0; r < 16; ++r) o[d][r] = 0.f;
;     float mrun = -1e30f, lrun = 0.f;
;     const int koff = swap23(i) * KT_PITCH + 16 * hi, voff = KT_BYTES + i * VT_PITCH + 16 * hi;
.LBB0_677:
	s_or_b64 exec, exec, s[10:11]
	s_mov_b32 s3, 0x66666667
	v_mul_hi_i32 v1, v0, s3
	v_lshrrev_b32_e32 v2, 31, v1
	v_ashrrev_i32_e32 v1, 3, v1
	v_add_u32_e32 v1, v1, v2
	v_mul_lo_u32 v2, v1, 20
	v_sub_u32_e32 v16, v0, v2
	v_add_u32_e32 v2, 0x200, v0
	v_mul_hi_i32 v3, v2, s3
	v_lshrrev_b32_e32 v4, 31, v3
	v_ashrrev_i32_e32 v3, 3, v3
	v_add_u32_e32 v17, v3, v4
	v_mul_lo_u32 v3, v17, 20
	v_sub_u32_e32 v18, v2, v3
	s_movk_i32 s3, 0x400
	v_mov_b32_e32 v2, 0xff
	v_bitop3_b16 v2, v0, s3, v2 bitop3:0xec
	s_mov_b32 s3, 0xcccd
	v_mul_u32_u24_sdwa v3, v2, s3 dst_sel:DWORD dst_unused:UNUSED_PAD src0_sel:WORD_0 src1_sel:DWORD
	v_lshrrev_b32_e32 v19, 20, v3
	v_mul_lo_u16_e32 v3, 20, v19
	s_movk_i32 s3, 0xa0
	v_sub_u16_e32 v14, v2, v3
	v_mul_lo_u32 v2, v1, s3
	v_ashrrev_i32_e32 v3, 31, v2
	v_lshlrev_b32_e32 v6, 3, v16
	v_mul_lo_u32 v8, v17, s3
	v_lshlrev_b64 v[2:3], 1, v[2:3]
	v_ashrrev_i32_e32 v7, 31, v6
	v_ashrrev_i32_e32 v9, 31, v8
	v_lshlrev_b32_e32 v12, 3, v18
	v_lshl_add_u64 v[4:5], s[0:1], 0, v[2:3]
	v_lshlrev_b64 v[6:7], 1, v[6:7]
	v_lshlrev_b64 v[8:9], 1, v[8:9]
	v_ashrrev_i32_e32 v13, 31, v12
	v_lshl_add_u64 v[4:5], v[4:5], 0, v[6:7]
	v_lshl_add_u64 v[10:11], s[0:1], 0, v[8:9]
	v_lshlrev_b64 v[12:13], 1, v[12:13]
	v_lshl_add_u64 v[10:11], v[10:11], 0, v[12:13]
	global_load_dwordx4 v[136:139], v[4:5], off
	global_load_dwordx4 v[140:143], v[10:11], off
	v_mul_u32_u24_e32 v4, 0xa0, v19
	v_lshlrev_b32_e32 v4, 1, v4
	v_mov_b32_e32 v5, v157
	v_lshl_add_u64 v[10:11], s[0:1], 0, v[4:5]
	v_lshlrev_b32_e32 v166, 4, v14
	v_mov_b32_e32 v167, v157
	v_ashrrev_i32_e32 v20, 3, v0
	v_lshl_add_u64 v[10:11], v[10:11], 0, v[166:167]
	v_add_u32_e32 v21, 64, v20
	global_load_dwordx4 v[144:147], v[10:11], off
	v_mad_i64_i32 v[10:11], s[10:11], s8, v20, 0
	v_lshlrev_b32_e32 v14, 4, v0
	v_lshl_add_u64 v[10:11], v[10:11], 1, s[6:7]
	v_and_b32_e32 v168, 0x70, v14
	v_mov_b32_e32 v169, v157
	v_mad_i64_i32 v[14:15], s[10:11], s8, v21, 0
	v_lshl_add_u64 v[10:11], v[10:11], 0, v[168:169]
	v_lshl_add_u64 v[14:15], v[14:15], 1, s[6:7]
	v_lshl_add_u64 v[14:15], v[14:15], 0, v[168:169]
	global_load_dwordx4 v[148:151], v[10:11], off
	global_load_dwordx4 v[152:155], v[14:15], off
	v_and_b32_e32 v10, 19, v0
	v_lshlrev_b32_e32 v11, 1, v181
	v_lshrrev_b32_e32 v0, 1, v0
	s_add_u32 s6, s6, 0x80
	s_movk_i32 s3, 0x90
	v_mul_lo_u32 v184, v20, s3
	v_and_b32_e32 v11, 8, v11
	v_and_b32_e32 v0, 4, v0
	s_addc_u32 s7, s7, 0
	s_lshl_b32 s3, s8, 1
	s_movk_i32 s8, 0x150
	v_or3_b32 v0, v10, v11, v0
	v_mul_lo_u32 v186, v1, s8
	v_lshlrev_b32_e32 v190, 4, v16
	v_mul_u32_u24_e32 v187, 0x150, v0
	v_mul_lo_u32 v189, v17, s8
	v_add_u32_e32 v0, v186, v190
	v_lshlrev_b32_e32 v191, 4, v18
	v_mad_u32_u24 v1, v19, s8, v166
	v_add_u32_e32 v14, v184, v168
	v_add_u32_e32 v10, v189, v191
	v_mov_b32_e32 v32, v157
	v_mov_b32_e32 v33, v157
	v_mov_b32_e32 v46, v157
	v_mov_b32_e32 v47, v157
	v_mul_u32_u24_e32 v188, 0x150, v19
	v_mov_b32_e32 v34, v157
	v_mov_b32_e32 v35, v157
	v_mov_b32_e32 v36, v157
	v_mov_b32_e32 v37, v157
	v_mov_b32_e32 v38, v157
	v_mov_b32_e32 v39, v157
	v_mov_b32_e32 v40, v157
	v_mov_b32_e32 v41, v157
	v_mov_b32_e32 v42, v157
	v_mov_b32_e32 v43, v157
	v_mov_b32_e32 v44, v157
	v_mov_b32_e32 v45, v157
	v_mov_b64_e32 v[62:63], v[46:47]
	v_ashrrev_i32_e32 v163, 31, v162
	v_lshlrev_b32_e32 v164, 3, v183
	v_mul_u32_u24_e32 v165, 0x90, v181
	v_add_u32_e32 v185, 0x2400, v184
	v_mov_b64_e32 v[60:61], v[44:45]
	v_mov_b64_e32 v[58:59], v[42:43]
	s_waitcnt vmcnt(4)
	ds_write_b128 v0, v[136:139]
	s_waitcnt vmcnt(3)
	ds_write_b128 v10, v[140:143]
	s_waitcnt vmcnt(2)
	ds_write_b128 v1, v[144:147]
	s_waitcnt vmcnt(1)
	ds_write_b128 v14, v[148:151] offset:21504
	s_waitcnt vmcnt(0)
	ds_write_b128 v14, v[152:155] offset:30720
	v_mad_i64_i32 v[0:1], s[8:9], s3, v20, v[168:169]
	v_lshl_add_u64 v[170:171], s[6:7], 0, v[0:1]
	v_mad_i64_i32 v[0:1], s[8:9], s3, v21, v[168:169]
	v_lshl_add_u64 v[172:173], s[6:7], 0, v[0:1]
	v_lshl_add_u64 v[0:1], v[2:3], 0, v[6:7]
	s_mov_b64 s[6:7], 0x5000
	v_lshl_add_u64 v[174:175], v[0:1], 0, s[6:7]
	v_lshl_add_u64 v[0:1], v[8:9], 0, v[12:13]
	v_lshl_add_u64 v[176:177], v[0:1], 0, s[6:7]
	v_lshl_add_u64 v[0:1], v[4:5], 0, v[166:167]
	v_lshl_add_u64 v[178:179], v[0:1], 0, s[6:7]
	v_mov_b64_e32 v[16:17], v[32:33]
	v_mov_b64_e32 v[0:1], v[32:33]
	s_lshl_b32 s3, s89, 6
	s_mov_b32 s6, 0
	v_mov_b32_e32 v169, 0xf149f2ca
	v_mov_b32_e32 v167, 0
	v_mov_b64_e32 v[56:57], v[40:41]
	v_mov_b64_e32 v[54:55], v[38:39]
	v_mov_b64_e32 v[52:53], v[36:37]
	v_mov_b64_e32 v[50:51], v[34:35]
	v_mov_b64_e32 v[48:49], v[32:33]
	v_mov_b64_e32 v[18:19], v[34:35]
	v_mov_b64_e32 v[20:21], v[36:37]
	v_mov_b64_e32 v[22:23], v[38:39]
	v_mov_b64_e32 v[24:25], v[40:41]
	v_mov_b64_e32 v[26:27], v[42:43]
	v_mov_b64_e32 v[28:29], v[44:45]
	v_mov_b64_e32 v[30:31], v[46:47]
	v_mov_b64_e32 v[2:3], v[34:35]
	v_mov_b64_e32 v[4:5], v[36:37]
	v_mov_b64_e32 v[6:7], v[38:39]
	v_mov_b64_e32 v[8:9], v[40:41]
	v_mov_b64_e32 v[10:11], v[42:43]
	v_mov_b64_e32 v[12:13], v[44:45]
	v_mov_b64_e32 v[14:15], v[46:47]
	s_mov_b32 s7, 0
	s_mov_b64 s[40:41], s[0:1]
	v_add_u32_e32 v216, v186, v190
	v_add_u32_e32 v217, v189, v191
	v_add_u32_e32 v218, v188, v166
	v_add_u32_e32 v219, v184, v168
	v_add_u32_e32 v220, v185, v168
	v_mov_b32_e32 v169, 0
	s_mov_b32 s20, 0
	s_mov_b32 s22, 0
	s_mov_b32 s23, 0
	s_mov_b32 s24, 0x9c00
	s_cmp_gt_u32 s89, 1
	s_cbranch_scc0 .Lp_pro_noload
	global_load_dwordx4 v[232:235], v174, s[40:41]
	global_load_dwordx4 v[236:239], v176, s[40:41]
	global_load_dwordx4 v[240:243], v178, s[40:41]
	global_load_dwordx4 v[244:247], v[170:171], off
	global_load_dwordx4 v[248:251], v[172:173], off
	s_add_u32 s40, s40, 0x5000
	s_addc_u32 s41, s41, 0
	v_lshl_add_u64 v[170:171], v[170:171], 0, s[82:83]
	v_lshl_add_u64 v[172:173], v[172:173], 0, s[82:83]
	s_cmp_gt_u32 s89, 2
	s_cbranch_scc0 .Lp_pro_noload
	global_load_dwordx4 v[136:139], v174, s[40:41]
	global_load_dwordx4 v[140:143], v176, s[40:41]
	global_load_dwordx4 v[144:147], v178, s[40:41]
	global_load_dwordx4 v[148:151], v[170:171], off
	global_load_dwordx4 v[152:155], v[172:173], off
	s_add_u32 s40, s40, 0x5000
	s_addc_u32 s41, s41, 0
	v_lshl_add_u64 v[170:171], v[170:171], 0, s[82:83]
	v_lshl_add_u64 v[172:173], v[172:173], 0, s[82:83]
; #define LAS __attribute__((address_space(3)))
; #define A_STORE(buf) do { LAS unsigned char* bb = lds + (buf) * ABUF; \
;         *(LAS u32x4*)(bb + kr1 * KT_PITCH + kc1 * 16) = st[0]; *(LAS u32x4*)(bb + kr2 * KT_PITCH + kc2 * 16) = st[1]; *(LAS u32x4*)(bb + kr3 * KT_PITCH + kc3 * 16) = st[2]; \
;         *(LAS u32x4*)(bb + KT_BYTES + vd1 * VT_PITCH + vc * 16) = st[3]; *(LAS u32x4*)(bb + KT_BYTES + vd2 * VT_PITCH + vc * 16) = st[4]; } while (0)
; __device__ __forceinline__ void attn_unit(KParams& P, int l, const AUnit& U, LAS unsigned char* lds) {
;     ...
;     for (int t = 0; t < U.nt; ++t) {
;         const bool more = t + 1 < U.nt;
;         if (more) A_LOAD(t + 1);
;         const LAS unsigned char* bb = lds + (t & 1) * ABUF;
;         f32x16 p0, p1;
; #pragma unroll
;         for (int r = 0; r < 16; ++r) { p0[r] = 0.f; p1[r] = 0.f; }
; #pragma unroll
;         for (int s = 0; s < 10; ++s) {
;             const bf16x8 k0 = *(const LAS bf16x8*)(bb + koff + 32 * s), k1 = *(const LAS bf16x8*)(bb + koff + 32 * KT_PITCH + 32 * s);
;             p0 = __builtin_amdgcn_mfma_f32_32x32x16_bf16(k0, qf[s], p0, 0, 0, 0);
;             p1 = __builtin_amdgcn_mfma_f32_32x32x16_bf16(k1, qf[s], p1, 0, 0, 0);
;         }
;     ...
;         if (more) A_STORE((t + 1) & 1);
.Lp_pro_noload:
	s_waitcnt lgkmcnt(0)
	s_barrier
	v_add3_u32 v230, s23, v187, v156
	ds_read_b128 v[192:195], v230
	ds_read_b128 v[196:199], v230 offset:10752
	ds_read_b128 v[200:203], v230 offset:32
	ds_read_b128 v[204:207], v230 offset:10784
	ds_read_b128 v[208:211], v230 offset:64
	s_waitcnt lgkmcnt(4)
	v_mfma_f32_32x32x16_bf16 v[80:95], v[192:195], v[96:99], 0
	ds_read_b128 v[226:229], v230 offset:10816
	s_waitcnt lgkmcnt(4)
	v_mfma_f32_32x32x16_bf16 v[64:79], v[196:199], v[96:99], 0
	ds_read_b128 v[192:195], v230 offset:96
	s_waitcnt lgkmcnt(4)
	v_mfma_f32_32x32x16_bf16 v[80:95], v[200:203], v[100:103], v[80:95]
	ds_read_b128 v[196:199], v230 offset:10848
	s_waitcnt lgkmcnt(4)
	v_mfma_f32_32x32x16_bf16 v[64:79], v[204:207], v[100:103], v[64:79]
	ds_read_b128 v[200:203], v230 offset:128
	s_waitcnt lgkmcnt(4)
	v_mfma_f32_32x32x16_bf16 v[80:95], v[208:211], v[104:107], v[80:95]
	ds_read_b128 v[204:207], v230 offset:10880
	s_waitcnt lgkmcnt(4)
	v_mfma_f32_32x32x16_bf16 v[64:79], v[226:229], v[104:107], v[64:79]
	ds_read_b128 v[208:211], v230 offset:160
	s_waitcnt lgkmcnt(4)
	v_mfma_f32_32x32x16_bf16 v[80:95], v[192:195], v[108:111], v[80:95]
	ds_read_b128 v[226:229], v230 offset:10912
	s_waitcnt lgkmcnt(4)
	v_mfma_f32_32x32x16_bf16 v[64:79], v[196:199], v[108:111], v[64:79]
	ds_read_b128 v[192:195], v230 offset:192
	s_waitcnt lgkmcnt(4)
	v_mfma_f32_32x32x16_bf16 v[80:95], v[200:203], v[112:115], v[80:95]
	ds_read_b128 v[196:199], v230 offset:10944
	s_waitcnt lgkmcnt(4)
	v_mfma_f32_32x32x16_bf16 v[64:79], v[204:207], v[112:115], v[64:79]
	ds_read_b128 v[200:203], v230 offset:224
	s_waitcnt lgkmcnt(4)
	v_mfma_f32_32x32x16_bf16 v[80:95], v[208:211], v[116:119], v[80:95]
	ds_read_b128 v[204:207], v230 offset:10976
	s_waitcnt lgkmcnt(4)
	v_mfma_f32_32x32x16_bf16 v[64:79], v[226:229], v[116:119], v[64:79]
	ds_read_b128 v[208:211], v230 offset:256
	s_waitcnt lgkmcnt(4)
	v_mfma_f32_32x32x16_bf16 v[80:95], v[192:195], v[120:123], v[80:95]
	ds_read_b128 v[226:229], v230 offset:11008
	s_waitcnt lgkmcnt(4)
	v_mfma_f32_32x32x16_bf16 v[64:79], v[196:199], v[120:123], v[64:79]
	ds_read_b128 v[192:195], v230 offset:288
	s_waitcnt lgkmcnt(4)
	v_mfma_f32_32x32x16_bf16 v[80:95], v[200:203], v[124:127], v[80:95]
	ds_read_b128 v[196:199], v230 offset:11040
	s_waitcnt lgkmcnt(4)
	v_mfma_f32_32x32x16_bf16 v[64:79], v[204:207], v[124:127], v[64:79]
	s_waitcnt lgkmcnt(3)
	v_mfma_f32_32x32x16_bf16 v[80:95], v[208:211], v[128:131], v[80:95]
	s_waitcnt lgkmcnt(2)
	v_mfma_f32_32x32x16_bf16 v[64:79], v[226:229], v[128:131], v[64:79]
	s_waitcnt lgkmcnt(1)
	v_mfma_f32_32x32x16_bf16 v[80:95], v[192:195], v[132:135], v[80:95]
	s_waitcnt lgkmcnt(0)
	v_mfma_f32_32x32x16_bf16 v[64:79], v[196:199], v[132:135], v[64:79]
	s_add_i32 s25, s20, 2
	s_cmp_lt_u32 s25, s89
	s_cbranch_scc1 .Lp_w5_t0
	s_waitcnt vmcnt(0)
	s_branch .Lp_wd_t0
.Lp_w5_t0:
	s_waitcnt vmcnt(5)
.Lp_wd_t0:
	s_add_i32 s25, s20, 3
	s_bitcmp1_b32 s20, 0
	s_cbranch_scc1 .Lp_set0_t0
	v_add_u32_e32 v221, s24, v216
	ds_write_b128 v221, v[232:235]
	v_add_u32_e32 v221, s24, v217
	ds_write_b128 v221, v[236:239]
	v_add_u32_e32 v221, s24, v218
	ds_write_b128 v221, v[240:243]
	v_add_u32_e32 v221, s24, v219
	ds_write_b128 v221, v[244:247] offset:21504
	v_add_u32_e32 v221, s24, v220
	ds_write_b128 v221, v[248:251] offset:21504
	s_cmp_lt_u32 s25, s89
	s_cbranch_scc0 .Lp_noload_t0
	global_load_dwordx4 v[232:235], v174, s[40:41]
	global_load_dwordx4 v[236:239], v176, s[40:41]
	global_load_dwordx4 v[240:243], v178, s[40:41]
	global_load_dwordx4 v[244:247], v[170:171], off
	global_load_dwordx4 v[248:251], v[172:173], off
	s_branch .Lp_adv_t0
.Lp_set0_t0:
	v_add_u32_e32 v221, s24, v216
	ds_write_b128 v221, v[136:139]
	v_add_u32_e32 v221, s24, v217
	ds_write_b128 v221, v[140:143]
	v_add_u32_e32 v221, s24, v218
	ds_write_b128 v221, v[144:147]
	v_add_u32_e32 v221, s24, v219
	ds_write_b128 v221, v[148:151] offset:21504
	v_add_u32_e32 v221, s24, v220
	ds_write_b128 v221, v[152:155] offset:21504
	s_cmp_lt_u32 s25, s89
	s_cbranch_scc0 .Lp_noload_t0
	global_load_dwordx4 v[136:139], v174, s[40:41]
	global_load_dwordx4 v[140:143], v176, s[40:41]
	global_load_dwordx4 v[144:147], v178, s[40:41]
	global_load_dwordx4 v[148:151], v[170:171], off
	global_load_dwordx4 v[152:155], v[172:173], off
.Lp_adv_t0:
	s_add_u32 s40, s40, 0x5000
	s_addc_u32 s41, s41, 0
	v_lshl_add_u64 v[170:171], v[170:171], 0, s[82:83]
	v_lshl_add_u64 v[172:173], v[172:173], 0, s[82:83]
; __device__ __forceinline__ void attn_unit(KParams& P, int l, const AUnit& U, LAS unsigned char* lds) {
;     ...
;         if ((t + 1) * 64 > U.kvlen) {
;             const int kb0 = t * 64 + 8 * hi;
; #pragma unroll
;             for (int r = 0; r < 16; ++r) { const int kv = kb0 + 16 * (r >> 3) + (r & 7); if (kv >= U.kvlen) p0[r] = -INFINITY; if (kv + 32 >= U.kvlen) p1[r] = -INFINITY; }
;         }
;         float mx = fmaxf(p0[0], p1[0]);
; #pragma unroll
;         for (int r = 1; r < 16; ++r) mx = fmaxf(mx, fmaxf(p0[r], p1[r]));
;         { const auto rr = __builtin_amdgcn_permlane32_swap(__float_as_uint(mx), __float_as_uint(mx), false, false);
;           mx = fmaxf(__uint_as_float(rr[0]), __uint_as_float(rr[1])); }
;         const float mnew = fmaxf(mrun, mx); const float f = __builtin_amdgcn_exp2f(mrun - mnew); const bool grew = __any(mnew > mrun); mrun = mnew;
;         f32x2 ps2 = {0.f, 0.f}; const f32x2 nm2 = {-mnew, -mnew};
; #pragma unroll
;         for (int r = 0; r < 16; r += 2) { f32x2 a = (f32x2){p0[r], p0[r + 1]} + nm2, b = (f32x2){p1[r], p1[r + 1]} + nm2;
;             a[0] = __builtin_amdgcn_exp2f(a[0]); a[1] = __builtin_amdgcn_exp2f(a[1]); b[0] = __builtin_amdgcn_exp2f(b[0]); b[1] = __builtin_amdgcn_exp2f(b[1]);
;             p0[r] = a[0]; p0[r + 1] = a[1]; p1[r] = b[0]; p1[r + 1] = b[1]; ps2 += a; ps2 += b; }
;         const float ps = ps2[0] + ps2[1];
.Lp_noload_t0:
	s_waitcnt lgkmcnt(0)
	s_nop 15
	s_nop 3
	s_mov_b32 s28, 64
	s_cmp_le_u32 s28, s70
	s_cbranch_scc1 .Lp_nomask0
	s_mov_b32 s25, 0
	v_add_u32_e32 v252, s25, v164
	v_add_u32_e32 v253, 0, v252
	v_cmp_gt_u32_e32 vcc, s70, v253
	s_nop 1
	v_cndmask_b32_e32 v80, v225, v80, vcc
	v_add_u32_e32 v253, 1, v252
	v_cmp_gt_u32_e32 vcc, s70, v253
	s_nop 1
	v_cndmask_b32_e32 v81, v225, v81, vcc
	v_add_u32_e32 v253, 2, v252
	v_cmp_gt_u32_e32 vcc, s70, v253
	s_nop 1
	v_cndmask_b32_e32 v82, v225, v82, vcc
	v_add_u32_e32 v253, 3, v252
	v_cmp_gt_u32_e32 vcc, s70, v253
	s_nop 1
	v_cndmask_b32_e32 v83, v225, v83, vcc
	v_add_u32_e32 v253, 4, v252
	v_cmp_gt_u32_e32 vcc, s70, v253
	s_nop 1
	v_cndmask_b32_e32 v84, v225, v84, vcc
	v_add_u32_e32 v253, 5, v252
	v_cmp_gt_u32_e32 vcc, s70, v253
	s_nop 1
	v_cndmask_b32_e32 v85, v225, v85, vcc
	v_add_u32_e32 v253, 6, v252
	v_cmp_gt_u32_e32 vcc, s70, v253
	s_nop 1
	v_cndmask_b32_e32 v86, v225, v86, vcc
	v_add_u32_e32 v253, 7, v252
	v_cmp_gt_u32_e32 vcc, s70, v253
	s_nop 1
	v_cndmask_b32_e32 v87, v225, v87, vcc
	v_add_u32_e32 v253, 16, v252
	v_cmp_gt_u32_e32 vcc, s70, v253
	s_nop 1
	v_cndmask_b32_e32 v88, v225, v88, vcc
	v_add_u32_e32 v253, 17, v252
	v_cmp_gt_u32_e32 vcc, s70, v253
	s_nop 1
	v_cndmask_b32_e32 v89, v225, v89, vcc
	v_add_u32_e32 v253, 18, v252
	v_cmp_gt_u32_e32 vcc, s70, v253
	s_nop 1
	v_cndmask_b32_e32 v90, v225, v90, vcc
	v_add_u32_e32 v253, 19, v252
	v_cmp_gt_u32_e32 vcc, s70, v253
	s_nop 1
	v_cndmask_b32_e32 v91, v225, v91, vcc
	v_add_u32_e32 v253, 20, v252
	v_cmp_gt_u32_e32 vcc, s70, v253
	s_nop 1
	v_cndmask_b32_e32 v92, v225, v92, vcc
	v_add_u32_e32 v253, 21, v252
	v_cmp_gt_u32_e32 vcc, s70, v253
	s_nop 1
	v_cndmask_b32_e32 v93, v225, v93, vcc
	v_add_u32_e32 v253, 22, v252
	v_cmp_gt_u32_e32 vcc, s70, v253
	s_nop 1
	v_cndmask_b32_e32 v94, v225, v94, vcc
	v_add_u32_e32 v253, 23, v252
	v_cmp_gt_u32_e32 vcc, s70, v253
	s_nop 1
	v_cndmask_b32_e32 v95, v225, v95, vcc
	v_add_u32_e32 v252, s25, v164
	v_add_u32_e32 v253, 32, v252
	v_cmp_gt_u32_e32 vcc, s70, v253
	s_nop 1
	v_cndmask_b32_e32 v64, v225, v64, vcc
	v_add_u32_e32 v253, 33, v252
	v_cmp_gt_u32_e32 vcc, s70, v253
	s_nop 1
	v_cndmask_b32_e32 v65, v225, v65, vcc
	v_add_u32_e32 v253, 34, v252
	v_cmp_gt_u32_e32 vcc, s70, v253
	s_nop 1
	v_cndmask_b32_e32 v66, v225, v66, vcc
	v_add_u32_e32 v253, 35, v252
	v_cmp_gt_u32_e32 vcc, s70, v253
	s_nop 1
	v_cndmask_b32_e32 v67, v225, v67, vcc
	v_add_u32_e32 v253, 36, v252
	v_cmp_gt_u32_e32 vcc, s70, v253
	s_nop 1
	v_cndmask_b32_e32 v68, v225, v68, vcc
	v_add_u32_e32 v253, 37, v252
	v_cmp_gt_u32_e32 vcc, s70, v253
	s_nop 1
	v_cndmask_b32_e32 v69, v225, v69, vcc
	v_add_u32_e32 v253, 38, v252
	v_cmp_gt_u32_e32 vcc, s70, v253
	s_nop 1
	v_cndmask_b32_e32 v70, v225, v70, vcc
	v_add_u32_e32 v253, 39, v252
	v_cmp_gt_u32_e32 vcc, s70, v253
	s_nop 1
	v_cndmask_b32_e32 v71, v225, v71, vcc
	v_add_u32_e32 v253, 48, v252
	v_cmp_gt_u32_e32 vcc, s70, v253
	s_nop 1
	v_cndmask_b32_e32 v72, v225, v72, vcc
	v_add_u32_e32 v253, 49, v252
	v_cmp_gt_u32_e32 vcc, s70, v253
	s_nop 1
	v_cndmask_b32_e32 v73, v225, v73, vcc
	v_add_u32_e32 v253, 50, v252
	v_cmp_gt_u32_e32 vcc, s70, v253
	s_nop 1
	v_cndmask_b32_e32 v74, v225, v74, vcc
	v_add_u32_e32 v253, 51, v252
	v_cmp_gt_u32_e32 vcc, s70, v253
	s_nop 1
	v_cndmask_b32_e32 v75, v225, v75, vcc
	v_add_u32_e32 v253, 52, v252
	v_cmp_gt_u32_e32 vcc, s70, v253
	s_nop 1
	v_cndmask_b32_e32 v76, v225, v76, vcc
	v_add_u32_e32 v253, 53, v252
	v_cmp_gt_u32_e32 vcc, s70, v253
	s_nop 1
	v_cndmask_b32_e32 v77, v225, v77, vcc
	v_add_u32_e32 v253, 54, v252
	v_cmp_gt_u32_e32 vcc, s70, v253
	s_nop 1
	v_cndmask_b32_e32 v78, v225, v78, vcc
	v_add_u32_e32 v253, 55, v252
	v_cmp_gt_u32_e32 vcc, s70, v253
	s_nop 1
	v_cndmask_b32_e32 v79, v225, v79, vcc
.Lp_nomask0:
	v_sub_f32_e32 v80, v80, v169
	v_sub_f32_e32 v81, v81, v169
	v_sub_f32_e32 v82, v82, v169
	v_sub_f32_e32 v83, v83, v169
	v_sub_f32_e32 v84, v84, v169
	v_sub_f32_e32 v85, v85, v169
	v_sub_f32_e32 v86, v86, v169
	v_sub_f32_e32 v87, v87, v169
	v_sub_f32_e32 v88, v88, v169
	v_sub_f32_e32 v89, v89, v169
	v_sub_f32_e32 v90, v90, v169
	v_sub_f32_e32 v91, v91, v169
	v_sub_f32_e32 v92, v92, v169
	v_sub_f32_e32 v93, v93, v169
	v_sub_f32_e32 v94, v94, v169
	v_sub_f32_e32 v95, v95, v169
	v_max3_f32 v180, v80, v81, v82
	v_max3_f32 v182, v83, v84, v85
	v_max3_f32 v180, v180, v86, v87
	v_max3_f32 v182, v182, v88, v89
	v_max3_f32 v180, v180, v90, v91
	v_max3_f32 v182, v182, v92, v93
	v_max3_f32 v180, v180, v94, v95
	v_max_f32_e32 v180, v180, v182
	v_mov_b32_e32 v182, v180
	s_nop 1
	v_permlane32_swap_b32_e32 v180, v182
	v_max_f32_e32 v180, v180, v182
	v_mov_b32_e32 v252, v180
	v_sub_f32_e32 v64, v64, v169
	v_sub_f32_e32 v65, v65, v169
	v_sub_f32_e32 v66, v66, v169
	v_sub_f32_e32 v67, v67, v169
	v_sub_f32_e32 v68, v68, v169
	v_sub_f32_e32 v69, v69, v169
	v_sub_f32_e32 v70, v70, v169
	v_sub_f32_e32 v71, v71, v169
	v_sub_f32_e32 v72, v72, v169
	v_sub_f32_e32 v73, v73, v169
	v_sub_f32_e32 v74, v74, v169
	v_sub_f32_e32 v75, v75, v169
	v_sub_f32_e32 v76, v76, v169
	v_sub_f32_e32 v77, v77, v169
	v_sub_f32_e32 v78, v78, v169
	v_sub_f32_e32 v79, v79, v169
	v_max3_f32 v180, v64, v65, v66
	v_max3_f32 v182, v67, v68, v69
	v_max3_f32 v180, v180, v70, v71
	v_max3_f32 v182, v182, v72, v73
	v_max3_f32 v180, v180, v74, v75
	v_max3_f32 v182, v182, v76, v77
	v_max3_f32 v180, v180, v78, v79
	v_max_f32_e32 v180, v180, v182
	v_mov_b32_e32 v182, v180
	s_nop 1
	v_permlane32_swap_b32_e32 v180, v182
	v_max_f32_e32 v180, v180, v182
	v_max_f32_e32 v180, v180, v252
	v_sub_f32_e32 v80, v80, v180
	v_sub_f32_e32 v81, v81, v180
	v_sub_f32_e32 v82, v82, v180
	v_sub_f32_e32 v83, v83, v180
; #define LAS __attribute__((address_space(3)))
; __device__ __forceinline__ unsigned cvt_pk_bf16(float lo, float hi) { f32x2 v = {lo, hi}; bf16x2_t b = __builtin_convertvector(v, bf16x2_t); return __builtin_bit_cast(unsigned, b); }
; __device__ __forceinline__ void attn_unit(KParams& P, int l, const AUnit& U, LAS unsigned char* lds) {
;     ...
;         const float mnew = fmaxf(mrun, mx); const float f = __builtin_amdgcn_exp2f(mrun - mnew); const bool grew = __any(mnew > mrun); mrun = mnew;
;         f32x2 ps2 = {0.f, 0.f}; const f32x2 nm2 = {-mnew, -mnew};
; #pragma unroll
;         for (int r = 0; r < 16; r += 2) { f32x2 a = (f32x2){p0[r], p0[r + 1]} + nm2, b = (f32x2){p1[r], p1[r + 1]} + nm2;
;             a[0] = __builtin_amdgcn_exp2f(a[0]); a[1] = __builtin_amdgcn_exp2f(a[1]); b[0] = __builtin_amdgcn_exp2f(b[0]); b[1] = __builtin_amdgcn_exp2f(b[1]);
;             p0[r] = a[0]; p0[r + 1] = a[1]; p1[r] = b[0]; p1[r + 1] = b[1]; ps2 += a; ps2 += b; }
;         const float ps = ps2[0] + ps2[1];
;         lrun = lrun * f + ps;
;         if (grew) {
; #pragma unroll
;             for (int d = 0; d < 4; ++d)
; #pragma unroll
;                 for (int r = 0; r < 16; ++r) o[d][r] *= f;
;         }
;         bf16x8 pf[4];
;         { u32x4 w;
;           w.x = cvt_pk_bf16(p0[0], p0[1]); w.y = cvt_pk_bf16(p0[2], p0[3]); w.z = cvt_pk_bf16(p0[4], p0[5]); w.w = cvt_pk_bf16(p0[6], p0[7]); pf[0] = __builtin_bit_cast(bf16x8, w);
;           w.x = cvt_pk_bf16(p0[8], p0[9]); w.y = cvt_pk_bf16(p0[10], p0[11]); w.z = cvt_pk_bf16(p0[12], p0[13]); w.w = cvt_pk_bf16(p0[14], p0[15]); pf[1] = __builtin_bit_cast(bf16x8, w);
;           w.x = cvt_pk_bf16(p1[0], p1[1]); w.y = cvt_pk_bf16(p1[2], p1[3]); w.z = cvt_pk_bf16(p1[4], p1[5]); w.w = cvt_pk_bf16(p1[6], p1[7]); pf[2] = __builtin_bit_cast(bf16x8, w);
;           w.x = cvt_pk_bf16(p1[8], p1[9]); w.y = cvt_pk_bf16(p1[10], p1[11]); w.z = cvt_pk_bf16(p1[12], p1[13]); w.w = cvt_pk_bf16(p1[14], p1[15]); pf[3] = __builtin_bit_cast(bf16x8, w); }
; #pragma unroll
;         for (int d = 0; d < 4; ++d)
; #pragma unroll
;             for (int ks = 0; ks < 4; ++ks) {
;                 const bf16x8 vf = *(const LAS bf16x8*)(bb + voff + d * 32 * VT_PITCH + 32 * ks);
;                 o[d] = __builtin_amdgcn_mfma_f32_32x32x16_bf16(vf, pf[ks], o[d], 0, 0, 0);
;             }
	v_sub_f32_e32 v84, v84, v180
	v_sub_f32_e32 v85, v85, v180
	v_sub_f32_e32 v86, v86, v180
	v_sub_f32_e32 v87, v87, v180
	v_sub_f32_e32 v88, v88, v180
	v_sub_f32_e32 v89, v89, v180
	v_sub_f32_e32 v90, v90, v180
	v_sub_f32_e32 v91, v91, v180
	v_sub_f32_e32 v92, v92, v180
	v_sub_f32_e32 v93, v93, v180
	v_sub_f32_e32 v94, v94, v180
	v_sub_f32_e32 v95, v95, v180
	v_sub_f32_e32 v64, v64, v180
	v_sub_f32_e32 v65, v65, v180
	v_sub_f32_e32 v66, v66, v180
	v_sub_f32_e32 v67, v67, v180
	v_sub_f32_e32 v68, v68, v180
	v_sub_f32_e32 v69, v69, v180
	v_sub_f32_e32 v70, v70, v180
	v_sub_f32_e32 v71, v71, v180
	v_sub_f32_e32 v72, v72, v180
	v_sub_f32_e32 v73, v73, v180
	v_sub_f32_e32 v74, v74, v180
	v_sub_f32_e32 v75, v75, v180
	v_sub_f32_e32 v76, v76, v180
	v_sub_f32_e32 v77, v77, v180
	v_sub_f32_e32 v78, v78, v180
	v_sub_f32_e32 v79, v79, v180
	v_add_f32_e32 v169, v169, v180
	v_exp_f32_e32 v80, v80
	v_exp_f32_e32 v81, v81
	v_exp_f32_e32 v82, v82
	v_exp_f32_e32 v83, v83
	v_exp_f32_e32 v84, v84
	v_exp_f32_e32 v85, v85
	v_exp_f32_e32 v86, v86
	v_exp_f32_e32 v87, v87
	v_exp_f32_e32 v88, v88
	v_exp_f32_e32 v89, v89
	v_exp_f32_e32 v90, v90
	v_exp_f32_e32 v91, v91
	v_exp_f32_e32 v92, v92
	v_exp_f32_e32 v93, v93
	v_exp_f32_e32 v94, v94
	v_exp_f32_e32 v95, v95
	v_add_f32_e32 v252, v80, v81
	v_add_f32_e32 v253, v88, v89
	v_add_f32_e32 v252, v252, v82
	v_add_f32_e32 v253, v253, v90
	v_add_f32_e32 v252, v252, v83
	v_add_f32_e32 v253, v253, v91
	v_add_f32_e32 v252, v252, v84
	v_add_f32_e32 v253, v253, v92
	v_add_f32_e32 v252, v252, v85
	v_add_f32_e32 v253, v253, v93
	v_add_f32_e32 v252, v252, v86
	v_add_f32_e32 v253, v253, v94
	v_add_f32_e32 v252, v252, v87
	v_add_f32_e32 v253, v253, v95
	v_add_f32_e32 v252, v252, v253
	v_add_f32_e32 v167, v167, v252
	v_cvt_pk_bf16_f32 v80, v80, v81
	v_cvt_pk_bf16_f32 v81, v82, v83
	v_cvt_pk_bf16_f32 v82, v84, v85
	v_cvt_pk_bf16_f32 v83, v86, v87
	v_cvt_pk_bf16_f32 v84, v88, v89
	v_cvt_pk_bf16_f32 v85, v90, v91
	v_cvt_pk_bf16_f32 v86, v92, v93
	v_cvt_pk_bf16_f32 v87, v94, v95
	v_exp_f32_e32 v64, v64
	v_exp_f32_e32 v65, v65
	v_exp_f32_e32 v66, v66
	v_exp_f32_e32 v67, v67
	v_exp_f32_e32 v68, v68
	v_exp_f32_e32 v69, v69
	v_exp_f32_e32 v70, v70
	v_exp_f32_e32 v71, v71
	v_exp_f32_e32 v72, v72
	v_exp_f32_e32 v73, v73
	v_exp_f32_e32 v74, v74
	v_exp_f32_e32 v75, v75
	v_exp_f32_e32 v76, v76
	v_exp_f32_e32 v77, v77
	v_exp_f32_e32 v78, v78
	v_exp_f32_e32 v79, v79
	v_add_f32_e32 v252, v64, v65
	v_add_f32_e32 v253, v72, v73
	v_add_f32_e32 v252, v252, v66
	v_add_f32_e32 v253, v253, v74
	v_add_f32_e32 v252, v252, v67
	v_add_f32_e32 v253, v253, v75
	v_add_f32_e32 v252, v252, v68
	v_add_f32_e32 v253, v253, v76
	v_add_f32_e32 v252, v252, v69
	v_add_f32_e32 v253, v253, v77
	v_add_f32_e32 v252, v252, v70
	v_add_f32_e32 v253, v253, v78
	v_add_f32_e32 v252, v252, v71
	v_add_f32_e32 v253, v253, v79
	v_add_f32_e32 v252, v252, v253
	v_add_f32_e32 v167, v167, v252
	v_cvt_pk_bf16_f32 v64, v64, v65
	v_cvt_pk_bf16_f32 v65, v66, v67
	v_cvt_pk_bf16_f32 v66, v68, v69
	v_cvt_pk_bf16_f32 v67, v70, v71
	v_cvt_pk_bf16_f32 v68, v72, v73
	v_cvt_pk_bf16_f32 v69, v74, v75
	v_cvt_pk_bf16_f32 v70, v76, v77
	v_cvt_pk_bf16_f32 v71, v78, v79
	s_waitcnt lgkmcnt(0)
	s_barrier
	s_mov_b32 s20, 1
	s_mov_b32 s22, 0
	s_mov_b32 s23, 0x9c00
	s_mov_b32 s24, 0x13800
	s_cmp_gt_u32 s89, 1
	s_cbranch_scc0 .Lp_tail_plain
	v_add3_u32 v230, s23, v187, v156
	v_add3_u32 v231, s22, v165, v156
	ds_read_b128 v[192:195], v231 offset:21504
	ds_read_b128 v[196:199], v231 offset:21536
	ds_read_b128 v[200:203], v231 offset:26112
	ds_read_b128 v[204:207], v231 offset:26144
	ds_read_b128 v[208:211], v231 offset:30720
	s_waitcnt lgkmcnt(4)
	v_mfma_f32_32x32x16_bf16 v[48:63], v[192:195], v[80:83], v[48:63]
	ds_read_b128 v[226:229], v231 offset:30752
	s_waitcnt lgkmcnt(4)
	v_mfma_f32_32x32x16_bf16 v[48:63], v[196:199], v[84:87], v[48:63]
	ds_read_b128 v[192:195], v231 offset:35328
	s_waitcnt lgkmcnt(4)
	v_mfma_f32_32x32x16_bf16 v[32:47], v[200:203], v[80:83], v[32:47]
	ds_read_b128 v[196:199], v231 offset:35360
	s_waitcnt lgkmcnt(4)
	v_mfma_f32_32x32x16_bf16 v[32:47], v[204:207], v[84:87], v[32:47]
	ds_read_b128 v[200:203], v230
	s_waitcnt lgkmcnt(4)
	v_mfma_f32_32x32x16_bf16 v[16:31], v[208:211], v[80:83], v[16:31]
	ds_read_b128 v[204:207], v230 offset:32
	s_waitcnt lgkmcnt(4)
	v_mfma_f32_32x32x16_bf16 v[16:31], v[226:229], v[84:87], v[16:31]
	ds_read_b128 v[208:211], v230 offset:64
	s_waitcnt lgkmcnt(4)
	v_mfma_f32_32x32x16_bf16 v[0:15], v[192:195], v[80:83], v[0:15]
	ds_read_b128 v[226:229], v230 offset:96
	s_waitcnt lgkmcnt(4)
	v_mfma_f32_32x32x16_bf16 v[0:15], v[196:199], v[84:87], v[0:15]
	ds_read_b128 v[192:195], v230 offset:128
	s_waitcnt lgkmcnt(4)
	v_mfma_f32_32x32x16_bf16 v[80:95], v[200:203], v[96:99], 0
	ds_read_b128 v[196:199], v230 offset:160
	s_waitcnt lgkmcnt(4)
	v_mfma_f32_32x32x16_bf16 v[80:95], v[204:207], v[100:103], v[80:95]
	ds_read_b128 v[200:203], v230 offset:192
	s_waitcnt lgkmcnt(4)
	v_mfma_f32_32x32x16_bf16 v[80:95], v[208:211], v[104:107], v[80:95]
	ds_read_b128 v[204:207], v230 offset:224
	s_waitcnt lgkmcnt(4)
	v_mfma_f32_32x32x16_bf16 v[80:95], v[226:229], v[108:111], v[80:95]
	ds_read_b128 v[208:211], v230 offset:256
	s_waitcnt lgkmcnt(4)
	v_mfma_f32_32x32x16_bf16 v[80:95], v[192:195], v[112:115], v[80:95]
	ds_read_b128 v[226:229], v230 offset:288
	s_waitcnt lgkmcnt(4)
	v_mfma_f32_32x32x16_bf16 v[80:95], v[196:199], v[116:119], v[80:95]
	ds_read_b128 v[192:195], v231 offset:21568
	s_waitcnt lgkmcnt(4)
	v_mfma_f32_32x32x16_bf16 v[80:95], v[200:203], v[120:123], v[80:95]
	ds_read_b128 v[196:199], v231 offset:21600
	s_waitcnt lgkmcnt(4)
	v_mfma_f32_32x32x16_bf16 v[80:95], v[204:207], v[124:127], v[80:95]
	ds_read_b128 v[200:203], v231 offset:26176
	s_waitcnt lgkmcnt(4)
	v_mfma_f32_32x32x16_bf16 v[80:95], v[208:211], v[128:131], v[80:95]
	ds_read_b128 v[204:207], v231 offset:26208
	s_waitcnt lgkmcnt(4)
	v_mfma_f32_32x32x16_bf16 v[80:95], v[226:229], v[132:135], v[80:95]
	ds_read_b128 v[208:211], v231 offset:30784
	s_add_i32 s25, s20, 2
	s_cmp_lt_u32 s25, s89
	s_cbranch_scc1 .Lp_w5_pt
	s_waitcnt vmcnt(0)
	s_branch .Lp_wd_pt

; #define LAS __attribute__((address_space(3)))
; __device__ __forceinline__ void attn_unit(KParams& P, int l, const AUnit& U, LAS unsigned char* lds) {
;     ...
;         float mx = fmaxf(p0[0], p1[0]);
; #pragma unroll
;         for (int r = 1; r < 16; ++r) mx = fmaxf(mx, fmaxf(p0[r], p1[r]));
;         { const auto rr = __builtin_amdgcn_permlane32_swap(__float_as_uint(mx), __float_as_uint(mx), false, false);
;           mx = fmaxf(__uint_as_float(rr[0]), __uint_as_float(rr[1])); }
;         const float mnew = fmaxf(mrun, mx); const float f = __builtin_amdgcn_exp2f(mrun - mnew); const bool grew = __any(mnew > mrun); mrun = mnew;
;         f32x2 ps2 = {0.f, 0.f}; const f32x2 nm2 = {-mnew, -mnew};
; #pragma unroll
;         for (int r = 0; r < 16; r += 2) { f32x2 a = (f32x2){p0[r], p0[r + 1]} + nm2, b = (f32x2){p1[r], p1[r + 1]} + nm2;
;             a[0] = __builtin_amdgcn_exp2f(a[0]); a[1] = __builtin_amdgcn_exp2f(a[1]); b[0] = __builtin_amdgcn_exp2f(b[0]); b[1] = __builtin_amdgcn_exp2f(b[1]);
;             p0[r] = a[0]; p0[r + 1] = a[1]; p1[r] = b[0]; p1[r + 1] = b[1]; ps2 += a; ps2 += b; }
;         const float ps = ps2[0] + ps2[1];
;         lrun = lrun * f + ps;
;         if (grew) {
; #pragma unroll
;             for (int d = 0; d < 4; ++d)
; #pragma unroll
;                 for (int r = 0; r < 16; ++r) o[d][r] *= f;
;         }
;         bf16x8 pf[4];
;         { u32x4 w;
;           w.x = cvt_pk_bf16(p0[0], p0[1]); w.y = cvt_pk_bf16(p0[2], p0[3]); w.z = cvt_pk_bf16(p0[4], p0[5]); w.w = cvt_pk_bf16(p0[6], p0[7]); pf[0] = __builtin_bit_cast(bf16x8, w);
;           w.x = cvt_pk_bf16(p0[8], p0[9]); w.y = cvt_pk_bf16(p0[10], p0[11]); w.z = cvt_pk_bf16(p0[12], p0[13]); w.w = cvt_pk_bf16(p0[14], p0[15]); pf[1] = __builtin_bit_cast(bf16x8, w);
;           w.x = cvt_pk_bf16(p1[0], p1[1]); w.y = cvt_pk_bf16(p1[2], p1[3]); w.z = cvt_pk_bf16(p1[4], p1[5]); w.w = cvt_pk_bf16(p1[6], p1[7]); pf[2] = __builtin_bit_cast(bf16x8, w);
;           w.x = cvt_pk_bf16(p1[8], p1[9]); w.y = cvt_pk_bf16(p1[10], p1[11]); w.z = cvt_pk_bf16(p1[12], p1[13]); w.w = cvt_pk_bf16(p1[14], p1[15]); pf[3] = __builtin_bit_cast(bf16x8, w); }
; #pragma unroll
;         for (int d = 0; d < 4; ++d)
; #pragma unroll
;             for (int ks = 0; ks < 4; ++ks) {
;                 const bf16x8 vf = *(const LAS bf16x8*)(bb + voff + d * 32 * VT_PITCH + 32 * ks);
.Lp_top:
	v_add3_u32 v230, s23, v187, v156
	v_add3_u32 v231, s22, v165, v156
	s_waitcnt lgkmcnt(4)
	v_mfma_f32_32x32x16_bf16 v[48:63], v[192:195], v[80:83], v[48:63]
	ds_read_b128 v[226:229], v231 offset:30752
	v_sub_f32_e32 v64, v64, v169
	v_sub_f32_e32 v65, v65, v169
	v_sub_f32_e32 v66, v66, v169
	v_sub_f32_e32 v67, v67, v169
	v_sub_f32_e32 v68, v68, v169
	v_sub_f32_e32 v69, v69, v169
	s_waitcnt lgkmcnt(4)
	v_mfma_f32_32x32x16_bf16 v[48:63], v[196:199], v[84:87], v[48:63]
	ds_read_b128 v[192:195], v231 offset:35328
	v_sub_f32_e32 v70, v70, v169
	v_sub_f32_e32 v71, v71, v169
	v_sub_f32_e32 v72, v72, v169
	v_sub_f32_e32 v73, v73, v169
	v_sub_f32_e32 v74, v74, v169
	v_sub_f32_e32 v75, v75, v169
	s_waitcnt lgkmcnt(4)
	v_mfma_f32_32x32x16_bf16 v[32:47], v[200:203], v[80:83], v[32:47]
	ds_read_b128 v[196:199], v231 offset:35360
	v_sub_f32_e32 v76, v76, v169
	v_sub_f32_e32 v77, v77, v169
	v_sub_f32_e32 v78, v78, v169
	v_sub_f32_e32 v79, v79, v169
	v_max3_f32 v180, v64, v65, v66
	v_max3_f32 v182, v67, v68, v69
	s_waitcnt lgkmcnt(4)
	v_mfma_f32_32x32x16_bf16 v[32:47], v[204:207], v[84:87], v[32:47]
	ds_read_b128 v[200:203], v230
	v_max3_f32 v180, v180, v70, v71
	v_max3_f32 v182, v182, v72, v73
	v_max3_f32 v180, v180, v74, v75
	v_max3_f32 v182, v182, v76, v77
	v_max3_f32 v180, v180, v78, v79
	v_max_f32_e32 v180, v180, v182
	s_waitcnt lgkmcnt(4)
	v_mfma_f32_32x32x16_bf16 v[16:31], v[208:211], v[80:83], v[16:31]
	ds_read_b128 v[204:207], v230 offset:32
	v_mov_b32_e32 v182, v180
	s_nop 1
	v_permlane32_swap_b32_e32 v180, v182
	v_max_f32_e32 v180, v180, v182
	v_cmp_lt_f32_e32 vcc, 0x41000000, v180
	s_cbranch_vccnz .Lp_rtop
	s_waitcnt lgkmcnt(4)
	v_mfma_f32_32x32x16_bf16 v[16:31], v[226:229], v[84:87], v[16:31]
	ds_read_b128 v[208:211], v230 offset:64
	v_exp_f32_e32 v64, v64
	v_exp_f32_e32 v72, v72
	s_waitcnt lgkmcnt(4)
	v_mfma_f32_32x32x16_bf16 v[0:15], v[192:195], v[80:83], v[0:15]
	ds_read_b128 v[226:229], v230 offset:96
	v_exp_f32_e32 v65, v65
	v_exp_f32_e32 v73, v73
	s_waitcnt lgkmcnt(4)
	v_mfma_f32_32x32x16_bf16 v[0:15], v[196:199], v[84:87], v[0:15]
	ds_read_b128 v[192:195], v230 offset:128
	v_exp_f32_e32 v66, v66
	v_exp_f32_e32 v74, v74
	v_add_f32_e32 v252, v64, v65
	v_add_f32_e32 v253, v72, v73
	s_waitcnt lgkmcnt(4)
	v_mfma_f32_32x32x16_bf16 v[80:95], v[200:203], v[96:99], 0
	ds_read_b128 v[196:199], v230 offset:160
	v_exp_f32_e32 v67, v67
	v_exp_f32_e32 v75, v75
	v_add_f32_e32 v252, v252, v66
	v_add_f32_e32 v253, v253, v74
	s_waitcnt lgkmcnt(4)
	v_mfma_f32_32x32x16_bf16 v[80:95], v[204:207], v[100:103], v[80:95]
	ds_read_b128 v[200:203], v230 offset:192
	v_exp_f32_e32 v68, v68
	v_exp_f32_e32 v76, v76
	v_add_f32_e32 v252, v252, v67
	v_add_f32_e32 v253, v253, v75
	s_waitcnt lgkmcnt(4)
	v_mfma_f32_32x32x16_bf16 v[80:95], v[208:211], v[104:107], v[80:95]
	ds_read_b128 v[204:207], v230 offset:224
	v_exp_f32_e32 v69, v69
	v_exp_f32_e32 v77, v77
	v_add_f32_e32 v252, v252, v68
	v_add_f32_e32 v253, v253, v76
	s_waitcnt lgkmcnt(4)
	v_mfma_f32_32x32x16_bf16 v[80:95], v[226:229], v[108:111], v[80:95]
	ds_read_b128 v[208:211], v230 offset:256
	v_exp_f32_e32 v70, v70
	v_exp_f32_e32 v78, v78
	v_add_f32_e32 v252, v252, v69
	v_add_f32_e32 v253, v253, v77
	s_waitcnt lgkmcnt(4)
	v_mfma_f32_32x32x16_bf16 v[80:95], v[192:195], v[112:115], v[80:95]
	ds_read_b128 v[226:229], v230 offset:288
	v_exp_f32_e32 v71, v71
	v_exp_f32_e32 v79, v79
	v_add_f32_e32 v252, v252, v70
	v_add_f32_e32 v253, v253, v78
	s_waitcnt lgkmcnt(4)
	v_mfma_f32_32x32x16_bf16 v[80:95], v[196:199], v[116:119], v[80:95]
	ds_read_b128 v[192:195], v231 offset:21568
	v_add_f32_e32 v252, v252, v71
	v_add_f32_e32 v253, v253, v79
	v_cvt_pk_bf16_f32 v64, v64, v65
	v_cvt_pk_bf16_f32 v65, v66, v67
	s_waitcnt lgkmcnt(4)
	v_mfma_f32_32x32x16_bf16 v[80:95], v[200:203], v[120:123], v[80:95]
	ds_read_b128 v[196:199], v231 offset:21600
	v_add_f32_e32 v252, v252, v253
	v_cvt_pk_bf16_f32 v66, v68, v69
	v_cvt_pk_bf16_f32 v67, v70, v71
	s_waitcnt lgkmcnt(4)
	v_mfma_f32_32x32x16_bf16 v[80:95], v[204:207], v[124:127], v[80:95]
	ds_read_b128 v[200:203], v231 offset:26176
	v_add_f32_e32 v167, v167, v252
	v_cvt_pk_bf16_f32 v68, v72, v73
	v_cvt_pk_bf16_f32 v69, v74, v75
	s_waitcnt lgkmcnt(4)
	v_mfma_f32_32x32x16_bf16 v[80:95], v[208:211], v[128:131], v[80:95]
	ds_read_b128 v[204:207], v231 offset:26208
	v_cvt_pk_bf16_f32 v70, v76, v77
	v_cvt_pk_bf16_f32 v71, v78, v79
	s_waitcnt lgkmcnt(4)
	v_mfma_f32_32x32x16_bf16 v[80:95], v[226:229], v[132:135], v[80:95]
	ds_read_b128 v[208:211], v231 offset:30784
	s_add_i32 s25, s20, 2
	s_cmp_lt_u32 s25, s89
	s_cbranch_scc1 .Lp_w5_lt
	s_waitcnt vmcnt(0)
	s_branch .Lp_wd_lt

; #define LAS __attribute__((address_space(3)))
; __device__ __forceinline__ void attn_unit(KParams& P, int l, const AUnit& U, LAS unsigned char* lds) {
;     ...
;         float mx = fmaxf(p0[0], p1[0]);
; #pragma unroll
;         for (int r = 1; r < 16; ++r) mx = fmaxf(mx, fmaxf(p0[r], p1[r]));
;         { const auto rr = __builtin_amdgcn_permlane32_swap(__float_as_uint(mx), __float_as_uint(mx), false, false);
;           mx = fmaxf(__uint_as_float(rr[0]), __uint_as_float(rr[1])); }
;         const float mnew = fmaxf(mrun, mx); const float f = __builtin_amdgcn_exp2f(mrun - mnew); const bool grew = __any(mnew > mrun); mrun = mnew;
;         f32x2 ps2 = {0.f, 0.f}; const f32x2 nm2 = {-mnew, -mnew};
; #pragma unroll
;         for (int r = 0; r < 16; r += 2) { f32x2 a = (f32x2){p0[r], p0[r + 1]} + nm2, b = (f32x2){p1[r], p1[r + 1]} + nm2;
;             a[0] = __builtin_amdgcn_exp2f(a[0]); a[1] = __builtin_amdgcn_exp2f(a[1]); b[0] = __builtin_amdgcn_exp2f(b[0]); b[1] = __builtin_amdgcn_exp2f(b[1]);
;             p0[r] = a[0]; p0[r + 1] = a[1]; p1[r] = b[0]; p1[r + 1] = b[1]; ps2 += a; ps2 += b; }
;         const float ps = ps2[0] + ps2[1];
;         lrun = lrun * f + ps;
;         if (grew) {
; #pragma unroll
;             for (int d = 0; d < 4; ++d)
; #pragma unroll
;                 for (int r = 0; r < 16; ++r) o[d][r] *= f;
;         }
;         bf16x8 pf[4];
;         { u32x4 w;
;           w.x = cvt_pk_bf16(p0[0], p0[1]); w.y = cvt_pk_bf16(p0[2], p0[3]); w.z = cvt_pk_bf16(p0[4], p0[5]); w.w = cvt_pk_bf16(p0[6], p0[7]); pf[0] = __builtin_bit_cast(bf16x8, w);
;           w.x = cvt_pk_bf16(p0[8], p0[9]); w.y = cvt_pk_bf16(p0[10], p0[11]); w.z = cvt_pk_bf16(p0[12], p0[13]); w.w = cvt_pk_bf16(p0[14], p0[15]); pf[1] = __builtin_bit_cast(bf16x8, w);
;           w.x = cvt_pk_bf16(p1[0], p1[1]); w.y = cvt_pk_bf16(p1[2], p1[3]); w.z = cvt_pk_bf16(p1[4], p1[5]); w.w = cvt_pk_bf16(p1[6], p1[7]); pf[2] = __builtin_bit_cast(bf16x8, w);
;           w.x = cvt_pk_bf16(p1[8], p1[9]); w.y = cvt_pk_bf16(p1[10], p1[11]); w.z = cvt_pk_bf16(p1[12], p1[13]); w.w = cvt_pk_bf16(p1[14], p1[15]); pf[3] = __builtin_bit_cast(bf16x8, w); }
; #pragma unroll
;         for (int d = 0; d < 4; ++d)
; #pragma unroll
;             for (int ks = 0; ks < 4; ++ks) {
;                 const bf16x8 vf = *(const LAS bf16x8*)(bb + voff + d * 32 * VT_PITCH + 32 * ks);
.Lp_noload_lt:
.Lp_mid:
	s_lshl_b32 s25, s20, 6
	s_add_i32 s28, s25, 64
	s_cmp_le_u32 s28, s70
	s_cbranch_scc0 .Lp_maskmid
.Lp_maskmid_ret:
	v_add3_u32 v230, s23, v187, v156
	v_add3_u32 v231, s22, v165, v156
	v_add3_u32 v221, s23, v165, v156
	s_waitcnt lgkmcnt(9)
	v_mfma_f32_32x32x16_bf16 v[48:63], v[192:195], v[64:67], v[48:63]
	ds_read_b128 v[226:229], v231 offset:30816
	v_sub_f32_e32 v80, v80, v169
	v_sub_f32_e32 v81, v81, v169
	v_sub_f32_e32 v82, v82, v169
	v_sub_f32_e32 v83, v83, v169
	v_sub_f32_e32 v84, v84, v169
	v_sub_f32_e32 v85, v85, v169
	s_waitcnt lgkmcnt(9)
	v_mfma_f32_32x32x16_bf16 v[48:63], v[196:199], v[68:71], v[48:63]
	ds_read_b128 v[192:195], v231 offset:35392
	v_sub_f32_e32 v86, v86, v169
	v_sub_f32_e32 v87, v87, v169
	v_sub_f32_e32 v88, v88, v169
	v_sub_f32_e32 v89, v89, v169
	v_sub_f32_e32 v90, v90, v169
	v_sub_f32_e32 v91, v91, v169
	s_waitcnt lgkmcnt(9)
	v_mfma_f32_32x32x16_bf16 v[32:47], v[200:203], v[64:67], v[32:47]
	ds_read_b128 v[196:199], v231 offset:35424
	v_sub_f32_e32 v92, v92, v169
	v_sub_f32_e32 v93, v93, v169
	v_sub_f32_e32 v94, v94, v169
	v_sub_f32_e32 v95, v95, v169
	v_max3_f32 v180, v80, v81, v82
	v_max3_f32 v182, v83, v84, v85
	s_waitcnt lgkmcnt(9)
	v_mfma_f32_32x32x16_bf16 v[32:47], v[204:207], v[68:71], v[32:47]
	ds_read_b128 v[200:203], v230 offset:10752
	v_max3_f32 v180, v180, v86, v87
	v_max3_f32 v182, v182, v88, v89
	v_max3_f32 v180, v180, v90, v91
	v_max3_f32 v182, v182, v92, v93
	v_max3_f32 v180, v180, v94, v95
	v_max_f32_e32 v180, v180, v182
	s_waitcnt lgkmcnt(9)
	v_mfma_f32_32x32x16_bf16 v[16:31], v[208:211], v[64:67], v[16:31]
	ds_read_b128 v[204:207], v230 offset:10784
	v_mov_b32_e32 v182, v180
	s_nop 1
	v_permlane32_swap_b32_e32 v180, v182
	v_max_f32_e32 v180, v180, v182
	v_cmp_lt_f32_e32 vcc, 0x41000000, v180
	s_cbranch_vccnz .Lp_rmid
	s_waitcnt lgkmcnt(4)
	v_mfma_f32_32x32x16_bf16 v[16:31], v[226:229], v[68:71], v[16:31]
	ds_read_b128 v[208:211], v230 offset:10816
	v_exp_f32_e32 v80, v80
	v_exp_f32_e32 v88, v88
	s_waitcnt lgkmcnt(4)
	v_mfma_f32_32x32x16_bf16 v[0:15], v[192:195], v[64:67], v[0:15]
	ds_read_b128 v[226:229], v230 offset:10848
	v_exp_f32_e32 v81, v81
	v_exp_f32_e32 v89, v89
	s_waitcnt lgkmcnt(4)
	v_mfma_f32_32x32x16_bf16 v[0:15], v[196:199], v[68:71], v[0:15]
	ds_read_b128 v[192:195], v230 offset:10880
	v_exp_f32_e32 v82, v82
	v_exp_f32_e32 v90, v90
	v_add_f32_e32 v252, v80, v81
	v_add_f32_e32 v253, v88, v89
	s_waitcnt lgkmcnt(4)
	v_mfma_f32_32x32x16_bf16 v[64:79], v[200:203], v[96:99], 0
	ds_read_b128 v[196:199], v230 offset:10912
	v_exp_f32_e32 v83, v83
	v_exp_f32_e32 v91, v91
	v_add_f32_e32 v252, v252, v82
	v_add_f32_e32 v253, v253, v90
	s_waitcnt lgkmcnt(4)
	v_mfma_f32_32x32x16_bf16 v[64:79], v[204:207], v[100:103], v[64:79]
	ds_read_b128 v[200:203], v230 offset:10944
	v_exp_f32_e32 v84, v84
	v_exp_f32_e32 v92, v92
	v_add_f32_e32 v252, v252, v83
	v_add_f32_e32 v253, v253, v91
	s_waitcnt lgkmcnt(4)
	v_mfma_f32_32x32x16_bf16 v[64:79], v[208:211], v[104:107], v[64:79]
	ds_read_b128 v[204:207], v230 offset:10976
	v_exp_f32_e32 v85, v85
	v_exp_f32_e32 v93, v93
	v_add_f32_e32 v252, v252, v84
	v_add_f32_e32 v253, v253, v92
	s_waitcnt lgkmcnt(4)
	v_mfma_f32_32x32x16_bf16 v[64:79], v[226:229], v[108:111], v[64:79]
	ds_read_b128 v[208:211], v230 offset:11008
	v_exp_f32_e32 v86, v86
	v_exp_f32_e32 v94, v94
	v_add_f32_e32 v252, v252, v85
	v_add_f32_e32 v253, v253, v93
	s_waitcnt lgkmcnt(4)
	v_mfma_f32_32x32x16_bf16 v[64:79], v[192:195], v[112:115], v[64:79]
	ds_read_b128 v[226:229], v230 offset:11040
	v_exp_f32_e32 v87, v87
	v_exp_f32_e32 v95, v95
	v_add_f32_e32 v252, v252, v86
	v_add_f32_e32 v253, v253, v94
	s_waitcnt lgkmcnt(4)
	v_mfma_f32_32x32x16_bf16 v[64:79], v[196:199], v[116:119], v[64:79]
	ds_read_b128 v[192:195], v221 offset:21504
	v_add_f32_e32 v252, v252, v87
	v_add_f32_e32 v253, v253, v95
	v_cvt_pk_bf16_f32 v80, v80, v81
	v_cvt_pk_bf16_f32 v81, v82, v83
	s_waitcnt lgkmcnt(4)
	v_mfma_f32_32x32x16_bf16 v[64:79], v[200:203], v[120:123], v[64:79]
	ds_read_b128 v[196:199], v221 offset:21536
	v_add_f32_e32 v252, v252, v253
	v_cvt_pk_bf16_f32 v82, v84, v85
	v_cvt_pk_bf16_f32 v83, v86, v87
	s_waitcnt lgkmcnt(4)
	v_mfma_f32_32x32x16_bf16 v[64:79], v[204:207], v[124:127], v[64:79]
	ds_read_b128 v[200:203], v221 offset:26112
	v_add_f32_e32 v167, v167, v252
	v_cvt_pk_bf16_f32 v84, v88, v89
	v_cvt_pk_bf16_f32 v85, v90, v91
	s_waitcnt lgkmcnt(4)
	v_mfma_f32_32x32x16_bf16 v[64:79], v[208:211], v[128:131], v[64:79]
	ds_read_b128 v[204:207], v221 offset:26144
	v_cvt_pk_bf16_f32 v86, v92, v93
	v_cvt_pk_bf16_f32 v87, v94, v95
	s_waitcnt lgkmcnt(4)
	v_mfma_f32_32x32x16_bf16 v[64:79], v[226:229], v[132:135], v[64:79]
	ds_read_b128 v[208:211], v221 offset:30720
; __device__ __forceinline__ void attn_unit(KParams& P, int l, const AUnit& U, LAS unsigned char* lds) {
;     ...
;         if ((t + 1) * 64 > U.kvlen) {
;             const int kb0 = t * 64 + 8 * hi;
; #pragma unroll
;             for (int r = 0; r < 16; ++r) { const int kv = kb0 + 16 * (r >> 3) + (r & 7); if (kv >= U.kvlen) p0[r] = -INFINITY; if (kv + 32 >= U.kvlen) p1[r] = -INFINITY; }
;         }
;         float mx = fmaxf(p0[0], p1[0]);
; #pragma unroll
;         for (int r = 1; r < 16; ++r) mx = fmaxf(mx, fmaxf(p0[r], p1[r]));
;         { const auto rr = __builtin_amdgcn_permlane32_swap(__float_as_uint(mx), __float_as_uint(mx), false, false);
;           mx = fmaxf(__uint_as_float(rr[0]), __uint_as_float(rr[1])); }
;         const float mnew = fmaxf(mrun, mx); const float f = __builtin_amdgcn_exp2f(mrun - mnew); const bool grew = __any(mnew > mrun); mrun = mnew;
;         f32x2 ps2 = {0.f, 0.f}; const f32x2 nm2 = {-mnew, -mnew};
; #pragma unroll
;         for (int r = 0; r < 16; r += 2) { f32x2 a = (f32x2){p0[r], p0[r + 1]} + nm2, b = (f32x2){p1[r], p1[r + 1]} + nm2;
;             a[0] = __builtin_amdgcn_exp2f(a[0]); a[1] = __builtin_amdgcn_exp2f(a[1]); b[0] = __builtin_amdgcn_exp2f(b[0]); b[1] = __builtin_amdgcn_exp2f(b[1]);
;             p0[r] = a[0]; p0[r + 1] = a[1]; p1[r] = b[0]; p1[r + 1] = b[1]; ps2 += a; ps2 += b; }
;         const float ps = ps2[0] + ps2[1];
;         lrun = lrun * f + ps;
;         if (grew) {
; #pragma unroll
;             for (int d = 0; d < 4; ++d)
; #pragma unroll
;                 for (int r = 0; r < 16; ++r) o[d][r] *= f;
;         }
.Lp_end:
	s_barrier
	s_nop 7
	s_mov_b32 s25, s22
	s_mov_b32 s22, s23
	s_mov_b32 s23, s24
	s_mov_b32 s24, s25
	s_add_i32 s20, s20, 1
	s_cmp_lt_u32 s20, s89
	s_cbranch_scc1 .Lp_top
	v_add3_u32 v231, s22, v165, v156
	s_waitcnt lgkmcnt(4)
	v_mfma_f32_32x32x16_bf16 v[48:63], v[192:195], v[80:83], v[48:63]
	ds_read_b128 v[226:229], v231 offset:30752
	s_waitcnt lgkmcnt(4)
	v_mfma_f32_32x32x16_bf16 v[48:63], v[196:199], v[84:87], v[48:63]
	ds_read_b128 v[192:195], v231 offset:35328
	s_waitcnt lgkmcnt(4)
	v_mfma_f32_32x32x16_bf16 v[32:47], v[200:203], v[80:83], v[32:47]
	ds_read_b128 v[196:199], v231 offset:35360
	s_waitcnt lgkmcnt(4)
	v_mfma_f32_32x32x16_bf16 v[32:47], v[204:207], v[84:87], v[32:47]
	s_waitcnt lgkmcnt(3)
	v_mfma_f32_32x32x16_bf16 v[16:31], v[208:211], v[80:83], v[16:31]
	s_waitcnt lgkmcnt(2)
	v_mfma_f32_32x32x16_bf16 v[16:31], v[226:229], v[84:87], v[16:31]
	s_waitcnt lgkmcnt(1)
	v_mfma_f32_32x32x16_bf16 v[0:15], v[192:195], v[80:83], v[0:15]
	s_waitcnt lgkmcnt(0)
	v_mfma_f32_32x32x16_bf16 v[0:15], v[196:199], v[84:87], v[0:15]
	s_waitcnt lgkmcnt(0)
	s_nop 15
	s_nop 3
	s_lshl_b32 s25, s89, 6
	s_cmp_le_u32 s25, s70
	s_cbranch_scc1 .Lp_nomaskt
	s_sub_u32 s25, s25, 64
	v_add_u32_e32 v252, s25, v164
	v_add_u32_e32 v253, 32, v252
	v_cmp_gt_u32_e32 vcc, s70, v253
	s_nop 1
	v_cndmask_b32_e32 v64, v225, v64, vcc
	v_add_u32_e32 v253, 33, v252
	v_cmp_gt_u32_e32 vcc, s70, v253
	s_nop 1
	v_cndmask_b32_e32 v65, v225, v65, vcc
	v_add_u32_e32 v253, 34, v252
	v_cmp_gt_u32_e32 vcc, s70, v253
	s_nop 1
	v_cndmask_b32_e32 v66, v225, v66, vcc
	v_add_u32_e32 v253, 35, v252
	v_cmp_gt_u32_e32 vcc, s70, v253
	s_nop 1
	v_cndmask_b32_e32 v67, v225, v67, vcc
	v_add_u32_e32 v253, 36, v252
	v_cmp_gt_u32_e32 vcc, s70, v253
	s_nop 1
	v_cndmask_b32_e32 v68, v225, v68, vcc
	v_add_u32_e32 v253, 37, v252
	v_cmp_gt_u32_e32 vcc, s70, v253
	s_nop 1
	v_cndmask_b32_e32 v69, v225, v69, vcc
	v_add_u32_e32 v253, 38, v252
	v_cmp_gt_u32_e32 vcc, s70, v253
	s_nop 1
	v_cndmask_b32_e32 v70, v225, v70, vcc
	v_add_u32_e32 v253, 39, v252
	v_cmp_gt_u32_e32 vcc, s70, v253
	s_nop 1
	v_cndmask_b32_e32 v71, v225, v71, vcc
	v_add_u32_e32 v253, 48, v252
	v_cmp_gt_u32_e32 vcc, s70, v253
	s_nop 1
	v_cndmask_b32_e32 v72, v225, v72, vcc
	v_add_u32_e32 v253, 49, v252
	v_cmp_gt_u32_e32 vcc, s70, v253
	s_nop 1
	v_cndmask_b32_e32 v73, v225, v73, vcc
	v_add_u32_e32 v253, 50, v252
	v_cmp_gt_u32_e32 vcc, s70, v253
	s_nop 1
	v_cndmask_b32_e32 v74, v225, v74, vcc
	v_add_u32_e32 v253, 51, v252
	v_cmp_gt_u32_e32 vcc, s70, v253
	s_nop 1
	v_cndmask_b32_e32 v75, v225, v75, vcc
	v_add_u32_e32 v253, 52, v252
	v_cmp_gt_u32_e32 vcc, s70, v253
	s_nop 1
	v_cndmask_b32_e32 v76, v225, v76, vcc
	v_add_u32_e32 v253, 53, v252
	v_cmp_gt_u32_e32 vcc, s70, v253
	s_nop 1
	v_cndmask_b32_e32 v77, v225, v77, vcc
	v_add_u32_e32 v253, 54, v252
	v_cmp_gt_u32_e32 vcc, s70, v253
	s_nop 1
	v_cndmask_b32_e32 v78, v225, v78, vcc
	v_add_u32_e32 v253, 55, v252
	v_cmp_gt_u32_e32 vcc, s70, v253
	s_nop 1
	v_cndmask_b32_e32 v79, v225, v79, vcc
.Lp_nomaskt:
	v_sub_f32_e32 v64, v64, v169
	v_sub_f32_e32 v65, v65, v169
	v_sub_f32_e32 v66, v66, v169
	v_sub_f32_e32 v67, v67, v169
	v_sub_f32_e32 v68, v68, v169
	v_sub_f32_e32 v69, v69, v169
	v_sub_f32_e32 v70, v70, v169
	v_sub_f32_e32 v71, v71, v169
	v_sub_f32_e32 v72, v72, v169
	v_sub_f32_e32 v73, v73, v169
	v_sub_f32_e32 v74, v74, v169
	v_sub_f32_e32 v75, v75, v169
	v_sub_f32_e32 v76, v76, v169
	v_sub_f32_e32 v77, v77, v169
	v_sub_f32_e32 v78, v78, v169
	v_sub_f32_e32 v79, v79, v169
	v_max3_f32 v180, v64, v65, v66
	v_max3_f32 v182, v67, v68, v69
	v_max3_f32 v180, v180, v70, v71
	v_max3_f32 v182, v182, v72, v73
	v_max3_f32 v180, v180, v74, v75
	v_max3_f32 v182, v182, v76, v77
	v_max3_f32 v180, v180, v78, v79
	v_max_f32_e32 v180, v180, v182
	v_mov_b32_e32 v182, v180
	s_nop 1
	v_permlane32_swap_b32_e32 v180, v182
	v_max_f32_e32 v180, v180, v182
	v_max_f32_e32 v180, 0, v180
	v_exp_f32_e64 v182, -v180
	s_nop 0
	v_pk_mul_f32 v[62:63], v[62:63], v[182:183] op_sel_hi:[1,0]
	v_pk_mul_f32 v[60:61], v[60:61], v[182:183] op_sel_hi:[1,0]
	v_pk_mul_f32 v[58:59], v[58:59], v[182:183] op_sel_hi:[1,0]
	v_pk_mul_f32 v[56:57], v[56:57], v[182:183] op_sel_hi:[1,0]
	v_pk_mul_f32 v[54:55], v[54:55], v[182:183] op_sel_hi:[1,0]
	v_pk_mul_f32 v[52:53], v[52:53], v[182:183] op_sel_hi:[1,0]
	v_pk_mul_f32 v[50:51], v[50:51], v[182:183] op_sel_hi:[1,0]
	v_pk_mul_f32 v[48:49], v[48:49], v[182:183] op_sel_hi:[1,0]
	v_pk_mul_f32 v[46:47], v[46:47], v[182:183] op_sel_hi:[1,0]
	v_pk_mul_f32 v[44:45], v[44:45], v[182:183] op_sel_hi:[1,0]
	v_pk_mul_f32 v[42:43], v[42:43], v[182:183] op_sel_hi:[1,0]
	v_pk_mul_f32 v[40:41], v[40:41], v[182:183] op_sel_hi:[1,0]
	v_pk_mul_f32 v[38:39], v[38:39], v[182:183] op_sel_hi:[1,0]
	v_pk_mul_f32 v[36:37], v[36:37], v[182:183] op_sel_hi:[1,0]
	v_pk_mul_f32 v[34:35], v[34:35], v[182:183] op_sel_hi:[1,0]
	v_pk_mul_f32 v[32:33], v[32:33], v[182:183] op_sel_hi:[1,0]
	v_pk_mul_f32 v[30:31], v[30:31], v[182:183] op_sel_hi:[1,0]
	v_pk_mul_f32 v[28:29], v[28:29], v[182:183] op_sel_hi:[1,0]
	v_pk_mul_f32 v[26:27], v[26:27], v[182:183] op_sel_hi:[1,0]
	v_pk_mul_f32 v[24:25], v[24:25], v[182:183] op_sel_hi:[1,0]
	v_pk_mul_f32 v[22:23], v[22:23], v[182:183] op_sel_hi:[1,0]
	v_pk_mul_f32 v[20:21], v[20:21], v[182:183] op_sel_hi:[1,0]
	v_pk_mul_f32 v[18:19], v[18:19], v[182:183] op_sel_hi:[1,0]
	v_pk_mul_f32 v[16:17], v[16:17], v[182:183] op_sel_hi:[1,0]
	v_pk_mul_f32 v[14:15], v[14:15], v[182:183] op_sel_hi:[1,0]
; #define LAS __attribute__((address_space(3)))
; __device__ __forceinline__ unsigned cvt_pk_bf16(float lo, float hi) { f32x2 v = {lo, hi}; bf16x2_t b = __builtin_convertvector(v, bf16x2_t); return __builtin_bit_cast(unsigned, b); }
; __device__ __forceinline__ void attn_unit(KParams& P, int l, const AUnit& U, LAS unsigned char* lds) {
;     ...
;         const float mnew = fmaxf(mrun, mx); const float f = __builtin_amdgcn_exp2f(mrun - mnew); const bool grew = __any(mnew > mrun); mrun = mnew;
;         f32x2 ps2 = {0.f, 0.f}; const f32x2 nm2 = {-mnew, -mnew};
; #pragma unroll
;         for (int r = 0; r < 16; r += 2) { f32x2 a = (f32x2){p0[r], p0[r + 1]} + nm2, b = (f32x2){p1[r], p1[r + 1]} + nm2;
;             a[0] = __builtin_amdgcn_exp2f(a[0]); a[1] = __builtin_amdgcn_exp2f(a[1]); b[0] = __builtin_amdgcn_exp2f(b[0]); b[1] = __builtin_amdgcn_exp2f(b[1]);
;             p0[r] = a[0]; p0[r + 1] = a[1]; p1[r] = b[0]; p1[r + 1] = b[1]; ps2 += a; ps2 += b; }
;         const float ps = ps2[0] + ps2[1];
;         lrun = lrun * f + ps;
;         if (grew) {
; #pragma unroll
;             for (int d = 0; d < 4; ++d)
; #pragma unroll
;                 for (int r = 0; r < 16; ++r) o[d][r] *= f;
;         }
;         bf16x8 pf[4];
;         { u32x4 w;
;           w.x = cvt_pk_bf16(p0[0], p0[1]); w.y = cvt_pk_bf16(p0[2], p0[3]); w.z = cvt_pk_bf16(p0[4], p0[5]); w.w = cvt_pk_bf16(p0[6], p0[7]); pf[0] = __builtin_bit_cast(bf16x8, w);
;           w.x = cvt_pk_bf16(p0[8], p0[9]); w.y = cvt_pk_bf16(p0[10], p0[11]); w.z = cvt_pk_bf16(p0[12], p0[13]); w.w = cvt_pk_bf16(p0[14], p0[15]); pf[1] = __builtin_bit_cast(bf16x8, w);
;           w.x = cvt_pk_bf16(p1[0], p1[1]); w.y = cvt_pk_bf16(p1[2], p1[3]); w.z = cvt_pk_bf16(p1[4], p1[5]); w.w = cvt_pk_bf16(p1[6], p1[7]); pf[2] = __builtin_bit_cast(bf16x8, w);
;           w.x = cvt_pk_bf16(p1[8], p1[9]); w.y = cvt_pk_bf16(p1[10], p1[11]); w.z = cvt_pk_bf16(p1[12], p1[13]); w.w = cvt_pk_bf16(p1[14], p1[15]); pf[3] = __builtin_bit_cast(bf16x8, w); }
; #pragma unroll
;         for (int d = 0; d < 4; ++d)
; #pragma unroll
;             for (int ks = 0; ks < 4; ++ks) {
;                 const bf16x8 vf = *(const LAS bf16x8*)(bb + voff + d * 32 * VT_PITCH + 32 * ks);
;                 o[d] = __builtin_amdgcn_mfma_f32_32x32x16_bf16(vf, pf[ks], o[d], 0, 0, 0);
;             }
	v_pk_mul_f32 v[12:13], v[12:13], v[182:183] op_sel_hi:[1,0]
	v_pk_mul_f32 v[10:11], v[10:11], v[182:183] op_sel_hi:[1,0]
	v_pk_mul_f32 v[8:9], v[8:9], v[182:183] op_sel_hi:[1,0]
	v_pk_mul_f32 v[6:7], v[6:7], v[182:183] op_sel_hi:[1,0]
	v_pk_mul_f32 v[4:5], v[4:5], v[182:183] op_sel_hi:[1,0]
	v_pk_mul_f32 v[2:3], v[2:3], v[182:183] op_sel_hi:[1,0]
	v_pk_mul_f32 v[0:1], v[0:1], v[182:183] op_sel_hi:[1,0]
	v_mul_f32_e32 v167, v167, v182
	v_sub_f32_e32 v64, v64, v180
	v_sub_f32_e32 v65, v65, v180
	v_sub_f32_e32 v66, v66, v180
	v_sub_f32_e32 v67, v67, v180
	v_sub_f32_e32 v68, v68, v180
	v_sub_f32_e32 v69, v69, v180
	v_sub_f32_e32 v70, v70, v180
	v_sub_f32_e32 v71, v71, v180
	v_sub_f32_e32 v72, v72, v180
	v_sub_f32_e32 v73, v73, v180
	v_sub_f32_e32 v74, v74, v180
	v_sub_f32_e32 v75, v75, v180
	v_sub_f32_e32 v76, v76, v180
	v_sub_f32_e32 v77, v77, v180
	v_sub_f32_e32 v78, v78, v180
	v_sub_f32_e32 v79, v79, v180
	v_add_f32_e32 v169, v169, v180
	v_exp_f32_e32 v64, v64
	v_exp_f32_e32 v65, v65
	v_exp_f32_e32 v66, v66
	v_exp_f32_e32 v67, v67
	v_exp_f32_e32 v68, v68
	v_exp_f32_e32 v69, v69
	v_exp_f32_e32 v70, v70
	v_exp_f32_e32 v71, v71
	v_exp_f32_e32 v72, v72
	v_exp_f32_e32 v73, v73
	v_exp_f32_e32 v74, v74
	v_exp_f32_e32 v75, v75
	v_exp_f32_e32 v76, v76
	v_exp_f32_e32 v77, v77
	v_exp_f32_e32 v78, v78
	v_exp_f32_e32 v79, v79
	v_add_f32_e32 v252, v64, v65
	v_add_f32_e32 v253, v72, v73
	v_add_f32_e32 v252, v252, v66
	v_add_f32_e32 v253, v253, v74
	v_add_f32_e32 v252, v252, v67
	v_add_f32_e32 v253, v253, v75
	v_add_f32_e32 v252, v252, v68
	v_add_f32_e32 v253, v253, v76
	v_add_f32_e32 v252, v252, v69
	v_add_f32_e32 v253, v253, v77
	v_add_f32_e32 v252, v252, v70
	v_add_f32_e32 v253, v253, v78
	v_add_f32_e32 v252, v252, v71
	v_add_f32_e32 v253, v253, v79
	v_add_f32_e32 v252, v252, v253
	v_add_f32_e32 v167, v167, v252
	v_cvt_pk_bf16_f32 v64, v64, v65
	v_cvt_pk_bf16_f32 v65, v66, v67
	v_cvt_pk_bf16_f32 v66, v68, v69
	v_cvt_pk_bf16_f32 v67, v70, v71
	v_cvt_pk_bf16_f32 v68, v72, v73
	v_cvt_pk_bf16_f32 v69, v74, v75
	v_cvt_pk_bf16_f32 v70, v76, v77
	v_cvt_pk_bf16_f32 v71, v78, v79
	v_add3_u32 v231, s22, v165, v156
	ds_read_b128 v[192:195], v231 offset:21568
	ds_read_b128 v[196:199], v231 offset:21600
	ds_read_b128 v[200:203], v231 offset:26176
	ds_read_b128 v[204:207], v231 offset:26208
	ds_read_b128 v[208:211], v231 offset:30784
	s_waitcnt lgkmcnt(4)
	v_mfma_f32_32x32x16_bf16 v[48:63], v[192:195], v[64:67], v[48:63]
	ds_read_b128 v[226:229], v231 offset:30816
	s_waitcnt lgkmcnt(4)
	v_mfma_f32_32x32x16_bf16 v[48:63], v[196:199], v[68:71], v[48:63]
	ds_read_b128 v[192:195], v231 offset:35392
	s_waitcnt lgkmcnt(4)
	v_mfma_f32_32x32x16_bf16 v[32:47], v[200:203], v[64:67], v[32:47]
	ds_read_b128 v[196:199], v231 offset:35424
	s_waitcnt lgkmcnt(4)
	v_mfma_f32_32x32x16_bf16 v[32:47], v[204:207], v[68:71], v[32:47]
	s_waitcnt lgkmcnt(3)
	v_mfma_f32_32x32x16_bf16 v[16:31], v[208:211], v[64:67], v[16:31]
	s_waitcnt lgkmcnt(2)
	v_mfma_f32_32x32x16_bf16 v[16:31], v[226:229], v[68:71], v[16:31]
	s_waitcnt lgkmcnt(1)
	v_mfma_f32_32x32x16_bf16 v[0:15], v[192:195], v[64:67], v[0:15]
	s_waitcnt lgkmcnt(0)
	v_mfma_f32_32x32x16_bf16 v[0:15], v[196:199], v[68:71], v[0:15]
	s_waitcnt lgkmcnt(0)
	s_branch .Lp_exit
.Lp_tail_plain:
	v_add3_u32 v231, s22, v165, v156
	ds_read_b128 v[192:195], v231 offset:21504
	ds_read_b128 v[196:199], v231 offset:21536
	ds_read_b128 v[200:203], v231 offset:26112
	ds_read_b128 v[204:207], v231 offset:26144
	ds_read_b128 v[208:211], v231 offset:30720
	s_waitcnt lgkmcnt(4)
	v_mfma_f32_32x32x16_bf16 v[48:63], v[192:195], v[80:83], v[48:63]
	ds_read_b128 v[226:229], v231 offset:30752
	s_waitcnt lgkmcnt(4)
	v_mfma_f32_32x32x16_bf16 v[48:63], v[196:199], v[84:87], v[48:63]
	ds_read_b128 v[192:195], v231 offset:35328
	s_waitcnt lgkmcnt(4)
	v_mfma_f32_32x32x16_bf16 v[32:47], v[200:203], v[80:83], v[32:47]
	ds_read_b128 v[196:199], v231 offset:35360
	s_waitcnt lgkmcnt(4)
	v_mfma_f32_32x32x16_bf16 v[32:47], v[204:207], v[84:87], v[32:47]
	ds_read_b128 v[200:203], v231 offset:21568
	s_waitcnt lgkmcnt(4)
	v_mfma_f32_32x32x16_bf16 v[16:31], v[208:211], v[80:83], v[16:31]
	ds_read_b128 v[204:207], v231 offset:21600
	s_waitcnt lgkmcnt(4)
	v_mfma_f32_32x32x16_bf16 v[16:31], v[226:229], v[84:87], v[16:31]
	ds_read_b128 v[208:211], v231 offset:26176
	s_waitcnt lgkmcnt(4)
	v_mfma_f32_32x32x16_bf16 v[0:15], v[192:195], v[80:83], v[0:15]
	ds_read_b128 v[226:229], v231 offset:26208
	s_waitcnt lgkmcnt(4)
	v_mfma_f32_32x32x16_bf16 v[0:15], v[196:199], v[84:87], v[0:15]
	ds_read_b128 v[192:195], v231 offset:30784
	s_waitcnt lgkmcnt(4)
	v_mfma_f32_32x32x16_bf16 v[48:63], v[200:203], v[64:67], v[48:63]
	ds_read_b128 v[196:199], v231 offset:30816
	s_waitcnt lgkmcnt(4)
	v_mfma_f32_32x32x16_bf16 v[48:63], v[204:207], v[68:71], v[48:63]
	ds_read_b128 v[200:203], v231 offset:35392
	s_waitcnt lgkmcnt(4)
	v_mfma_f32_32x32x16_bf16 v[32:47], v[208:211], v[64:67], v[32:47]
	ds_read_b128 v[204:207], v231 offset:35424
	s_waitcnt lgkmcnt(4)
	v_mfma_f32_32x32x16_bf16 v[32:47], v[226:229], v[68:71], v[32:47]
	s_waitcnt lgkmcnt(3)
	v_mfma_f32_32x32x16_bf16 v[16:31], v[192:195], v[64:67], v[16:31]
	s_waitcnt lgkmcnt(2)
	v_mfma_f32_32x32x16_bf16 v[16:31], v[196:199], v[68:71], v[16:31]
	s_waitcnt lgkmcnt(1)
	v_mfma_f32_32x32x16_bf16 v[0:15], v[200:203], v[64:67], v[0:15]
	s_waitcnt lgkmcnt(0)
	v_mfma_f32_32x32x16_bf16 v[0:15], v[204:207], v[68:71], v[0:15]
	s_waitcnt lgkmcnt(0)

; #define LAS __attribute__((address_space(3)))
; __device__ __forceinline__ void attn_unit(KParams& P, int l, const AUnit& U, LAS unsigned char* lds) {
;     ...
;         for (int s = 0; s < 10; ++s) {
;             const bf16x8 k0 = *(const LAS bf16x8*)(bb + koff + 32 * s), k1 = *(const LAS bf16x8*)(bb + koff + 32 * KT_PITCH + 32 * s);
;             p0 = __builtin_amdgcn_mfma_f32_32x32x16_bf16(k0, qf[s], p0, 0, 0, 0);
;             p1 = __builtin_amdgcn_mfma_f32_32x32x16_bf16(k1, qf[s], p1, 0, 0, 0);
;         }
;     ...
; #pragma unroll
;         for (int d = 0; d < 4; ++d)
; #pragma unroll
;             for (int ks = 0; ks < 4; ++ks) {
;                 const bf16x8 vf = *(const LAS bf16x8*)(bb + voff + d * 32 * VT_PITCH + 32 * ks);
;                 o[d] = __builtin_amdgcn_mfma_f32_32x32x16_bf16(vf, pf[ks], o[d], 0, 0, 0);
;             }
.Lp_rtop:
	s_waitcnt lgkmcnt(4)
	v_mfma_f32_32x32x16_bf16 v[16:31], v[226:229], v[84:87], v[16:31]
	ds_read_b128 v[208:211], v230 offset:64
	s_waitcnt lgkmcnt(4)
	v_mfma_f32_32x32x16_bf16 v[0:15], v[192:195], v[80:83], v[0:15]
	ds_read_b128 v[226:229], v230 offset:96
	s_waitcnt lgkmcnt(4)
	v_mfma_f32_32x32x16_bf16 v[0:15], v[196:199], v[84:87], v[0:15]
	ds_read_b128 v[192:195], v230 offset:128
	s_waitcnt lgkmcnt(4)
	v_mfma_f32_32x32x16_bf16 v[80:95], v[200:203], v[96:99], 0
	ds_read_b128 v[196:199], v230 offset:160
	s_waitcnt lgkmcnt(4)
	v_mfma_f32_32x32x16_bf16 v[80:95], v[204:207], v[100:103], v[80:95]
	ds_read_b128 v[200:203], v230 offset:192
	s_waitcnt lgkmcnt(4)
	v_mfma_f32_32x32x16_bf16 v[80:95], v[208:211], v[104:107], v[80:95]
	ds_read_b128 v[204:207], v230 offset:224
	s_waitcnt lgkmcnt(4)
	v_mfma_f32_32x32x16_bf16 v[80:95], v[226:229], v[108:111], v[80:95]
	ds_read_b128 v[208:211], v230 offset:256
	s_waitcnt lgkmcnt(4)
	v_mfma_f32_32x32x16_bf16 v[80:95], v[192:195], v[112:115], v[80:95]
	ds_read_b128 v[226:229], v230 offset:288
	s_waitcnt lgkmcnt(4)
	v_mfma_f32_32x32x16_bf16 v[80:95], v[196:199], v[116:119], v[80:95]
	ds_read_b128 v[192:195], v231 offset:21568
	s_waitcnt lgkmcnt(4)
	v_mfma_f32_32x32x16_bf16 v[80:95], v[200:203], v[120:123], v[80:95]
	ds_read_b128 v[196:199], v231 offset:21600
	s_waitcnt lgkmcnt(4)
	v_mfma_f32_32x32x16_bf16 v[80:95], v[204:207], v[124:127], v[80:95]
	ds_read_b128 v[200:203], v231 offset:26176
	s_waitcnt lgkmcnt(4)
	v_mfma_f32_32x32x16_bf16 v[80:95], v[208:211], v[128:131], v[80:95]
	ds_read_b128 v[204:207], v231 offset:26208
	s_waitcnt lgkmcnt(4)
	v_mfma_f32_32x32x16_bf16 v[80:95], v[226:229], v[132:135], v[80:95]
	ds_read_b128 v[208:211], v231 offset:30784
	s_add_i32 s25, s20, 2
	s_cmp_lt_u32 s25, s89
	s_cbranch_scc1 .Lp_w5_ltr
	s_waitcnt vmcnt(0)
	s_branch .Lp_wd_ltr

; #define LAS __attribute__((address_space(3)))
; __device__ __forceinline__ unsigned cvt_pk_bf16(float lo, float hi) { f32x2 v = {lo, hi}; bf16x2_t b = __builtin_convertvector(v, bf16x2_t); return __builtin_bit_cast(unsigned, b); }
; __device__ __forceinline__ void attn_unit(KParams& P, int l, const AUnit& U, LAS unsigned char* lds) {
;     ...
;         const float mnew = fmaxf(mrun, mx); const float f = __builtin_amdgcn_exp2f(mrun - mnew); const bool grew = __any(mnew > mrun); mrun = mnew;
;         f32x2 ps2 = {0.f, 0.f}; const f32x2 nm2 = {-mnew, -mnew};
; #pragma unroll
;         for (int r = 0; r < 16; r += 2) { f32x2 a = (f32x2){p0[r], p0[r + 1]} + nm2, b = (f32x2){p1[r], p1[r + 1]} + nm2;
;             a[0] = __builtin_amdgcn_exp2f(a[0]); a[1] = __builtin_amdgcn_exp2f(a[1]); b[0] = __builtin_amdgcn_exp2f(b[0]); b[1] = __builtin_amdgcn_exp2f(b[1]);
;             p0[r] = a[0]; p0[r + 1] = a[1]; p1[r] = b[0]; p1[r + 1] = b[1]; ps2 += a; ps2 += b; }
;         const float ps = ps2[0] + ps2[1];
;         lrun = lrun * f + ps;
;         if (grew) {
; #pragma unroll
;             for (int d = 0; d < 4; ++d)
; #pragma unroll
;                 for (int r = 0; r < 16; ++r) o[d][r] *= f;
;         }
;         bf16x8 pf[4];
;         { u32x4 w;
;           w.x = cvt_pk_bf16(p0[0], p0[1]); w.y = cvt_pk_bf16(p0[2], p0[3]); w.z = cvt_pk_bf16(p0[4], p0[5]); w.w = cvt_pk_bf16(p0[6], p0[7]); pf[0] = __builtin_bit_cast(bf16x8, w);
;           w.x = cvt_pk_bf16(p0[8], p0[9]); w.y = cvt_pk_bf16(p0[10], p0[11]); w.z = cvt_pk_bf16(p0[12], p0[13]); w.w = cvt_pk_bf16(p0[14], p0[15]); pf[1] = __builtin_bit_cast(bf16x8, w);
;           w.x = cvt_pk_bf16(p1[0], p1[1]); w.y = cvt_pk_bf16(p1[2], p1[3]); w.z = cvt_pk_bf16(p1[4], p1[5]); w.w = cvt_pk_bf16(p1[6], p1[7]); pf[2] = __builtin_bit_cast(bf16x8, w);
;           w.x = cvt_pk_bf16(p1[8], p1[9]); w.y = cvt_pk_bf16(p1[10], p1[11]); w.z = cvt_pk_bf16(p1[12], p1[13]); w.w = cvt_pk_bf16(p1[14], p1[15]); pf[3] = __builtin_bit_cast(bf16x8, w); }
; #pragma unroll
;         for (int d = 0; d < 4; ++d)
; #pragma unroll
;             for (int ks = 0; ks < 4; ++ks) {
;                 const bf16x8 vf = *(const LAS bf16x8*)(bb + voff + d * 32 * VT_PITCH + 32 * ks);
;                 o[d] = __builtin_amdgcn_mfma_f32_32x32x16_bf16(vf, pf[ks], o[d], 0, 0, 0);
;             }
.Lp_noload_ltr:
	s_nop 15
	s_nop 3
	v_max_f32_e32 v180, 0, v180
	v_exp_f32_e64 v182, -v180
	s_nop 0
	v_pk_mul_f32 v[62:63], v[62:63], v[182:183] op_sel_hi:[1,0]
	v_pk_mul_f32 v[60:61], v[60:61], v[182:183] op_sel_hi:[1,0]
	v_pk_mul_f32 v[58:59], v[58:59], v[182:183] op_sel_hi:[1,0]
	v_pk_mul_f32 v[56:57], v[56:57], v[182:183] op_sel_hi:[1,0]
	v_pk_mul_f32 v[54:55], v[54:55], v[182:183] op_sel_hi:[1,0]
	v_pk_mul_f32 v[52:53], v[52:53], v[182:183] op_sel_hi:[1,0]
	v_pk_mul_f32 v[50:51], v[50:51], v[182:183] op_sel_hi:[1,0]
	v_pk_mul_f32 v[48:49], v[48:49], v[182:183] op_sel_hi:[1,0]
	v_pk_mul_f32 v[46:47], v[46:47], v[182:183] op_sel_hi:[1,0]
	v_pk_mul_f32 v[44:45], v[44:45], v[182:183] op_sel_hi:[1,0]
	v_pk_mul_f32 v[42:43], v[42:43], v[182:183] op_sel_hi:[1,0]
	v_pk_mul_f32 v[40:41], v[40:41], v[182:183] op_sel_hi:[1,0]
	v_pk_mul_f32 v[38:39], v[38:39], v[182:183] op_sel_hi:[1,0]
	v_pk_mul_f32 v[36:37], v[36:37], v[182:183] op_sel_hi:[1,0]
	v_pk_mul_f32 v[34:35], v[34:35], v[182:183] op_sel_hi:[1,0]
	v_pk_mul_f32 v[32:33], v[32:33], v[182:183] op_sel_hi:[1,0]
	v_pk_mul_f32 v[30:31], v[30:31], v[182:183] op_sel_hi:[1,0]
	v_pk_mul_f32 v[28:29], v[28:29], v[182:183] op_sel_hi:[1,0]
	v_pk_mul_f32 v[26:27], v[26:27], v[182:183] op_sel_hi:[1,0]
	v_pk_mul_f32 v[24:25], v[24:25], v[182:183] op_sel_hi:[1,0]
	v_pk_mul_f32 v[22:23], v[22:23], v[182:183] op_sel_hi:[1,0]
	v_pk_mul_f32 v[20:21], v[20:21], v[182:183] op_sel_hi:[1,0]
	v_pk_mul_f32 v[18:19], v[18:19], v[182:183] op_sel_hi:[1,0]
	v_pk_mul_f32 v[16:17], v[16:17], v[182:183] op_sel_hi:[1,0]
	v_pk_mul_f32 v[14:15], v[14:15], v[182:183] op_sel_hi:[1,0]
	v_pk_mul_f32 v[12:13], v[12:13], v[182:183] op_sel_hi:[1,0]
	v_pk_mul_f32 v[10:11], v[10:11], v[182:183] op_sel_hi:[1,0]
	v_pk_mul_f32 v[8:9], v[8:9], v[182:183] op_sel_hi:[1,0]
	v_pk_mul_f32 v[6:7], v[6:7], v[182:183] op_sel_hi:[1,0]
	v_pk_mul_f32 v[4:5], v[4:5], v[182:183] op_sel_hi:[1,0]
	v_pk_mul_f32 v[2:3], v[2:3], v[182:183] op_sel_hi:[1,0]
	v_pk_mul_f32 v[0:1], v[0:1], v[182:183] op_sel_hi:[1,0]
	v_mul_f32_e32 v167, v167, v182
	v_sub_f32_e32 v64, v64, v180
	v_sub_f32_e32 v65, v65, v180
	v_sub_f32_e32 v66, v66, v180
	v_sub_f32_e32 v67, v67, v180
	v_sub_f32_e32 v68, v68, v180
	v_sub_f32_e32 v69, v69, v180
	v_sub_f32_e32 v70, v70, v180
	v_sub_f32_e32 v71, v71, v180
	v_sub_f32_e32 v72, v72, v180
	v_sub_f32_e32 v73, v73, v180
	v_sub_f32_e32 v74, v74, v180
	v_sub_f32_e32 v75, v75, v180
	v_sub_f32_e32 v76, v76, v180
	v_sub_f32_e32 v77, v77, v180
	v_sub_f32_e32 v78, v78, v180
	v_sub_f32_e32 v79, v79, v180
	v_add_f32_e32 v169, v169, v180
	v_exp_f32_e32 v64, v64
	v_exp_f32_e32 v65, v65
	v_exp_f32_e32 v66, v66
	v_exp_f32_e32 v67, v67
	v_exp_f32_e32 v68, v68
	v_exp_f32_e32 v69, v69
	v_exp_f32_e32 v70, v70
	v_exp_f32_e32 v71, v71
	v_exp_f32_e32 v72, v72
	v_exp_f32_e32 v73, v73
	v_exp_f32_e32 v74, v74
	v_exp_f32_e32 v75, v75
	v_exp_f32_e32 v76, v76
	v_exp_f32_e32 v77, v77
	v_exp_f32_e32 v78, v78
	v_exp_f32_e32 v79, v79
	v_add_f32_e32 v252, v64, v65
	v_add_f32_e32 v253, v72, v73
	v_add_f32_e32 v252, v252, v66
	v_add_f32_e32 v253, v253, v74
	v_add_f32_e32 v252, v252, v67
	v_add_f32_e32 v253, v253, v75
	v_add_f32_e32 v252, v252, v68
	v_add_f32_e32 v253, v253, v76
	v_add_f32_e32 v252, v252, v69
	v_add_f32_e32 v253, v253, v77
	v_add_f32_e32 v252, v252, v70
	v_add_f32_e32 v253, v253, v78
	v_add_f32_e32 v252, v252, v71
	v_add_f32_e32 v253, v253, v79
	v_add_f32_e32 v252, v252, v253
	v_add_f32_e32 v167, v167, v252
	v_cvt_pk_bf16_f32 v64, v64, v65
	v_cvt_pk_bf16_f32 v65, v66, v67
	v_cvt_pk_bf16_f32 v66, v68, v69
	v_cvt_pk_bf16_f32 v67, v70, v71
	v_cvt_pk_bf16_f32 v68, v72, v73
	v_cvt_pk_bf16_f32 v69, v74, v75
	v_cvt_pk_bf16_f32 v70, v76, v77
	v_cvt_pk_bf16_f32 v71, v78, v79
	s_branch .Lp_mid
.Lp_rmid:
	s_waitcnt lgkmcnt(4)
	v_mfma_f32_32x32x16_bf16 v[16:31], v[226:229], v[68:71], v[16:31]
	ds_read_b128 v[208:211], v230 offset:10816
	s_waitcnt lgkmcnt(4)
	v_mfma_f32_32x32x16_bf16 v[0:15], v[192:195], v[64:67], v[0:15]
	ds_read_b128 v[226:229], v230 offset:10848
	s_waitcnt lgkmcnt(4)
	v_mfma_f32_32x32x16_bf16 v[0:15], v[196:199], v[68:71], v[0:15]
	ds_read_b128 v[192:195], v230 offset:10880
	s_waitcnt lgkmcnt(4)
	v_mfma_f32_32x32x16_bf16 v[64:79], v[200:203], v[96:99], 0
	ds_read_b128 v[196:199], v230 offset:10912
	s_waitcnt lgkmcnt(4)
	v_mfma_f32_32x32x16_bf16 v[64:79], v[204:207], v[100:103], v[64:79]
	ds_read_b128 v[200:203], v230 offset:10944
	s_waitcnt lgkmcnt(4)
	v_mfma_f32_32x32x16_bf16 v[64:79], v[208:211], v[104:107], v[64:79]
	ds_read_b128 v[204:207], v230 offset:10976
	s_waitcnt lgkmcnt(4)
	v_mfma_f32_32x32x16_bf16 v[64:79], v[226:229], v[108:111], v[64:79]
	ds_read_b128 v[208:211], v230 offset:11008
	s_waitcnt lgkmcnt(4)
	v_mfma_f32_32x32x16_bf16 v[64:79], v[192:195], v[112:115], v[64:79]
	ds_read_b128 v[226:229], v230 offset:11040
	s_waitcnt lgkmcnt(4)
	v_mfma_f32_32x32x16_bf16 v[64:79], v[196:199], v[116:119], v[64:79]
	ds_read_b128 v[192:195], v221 offset:21504
	s_waitcnt lgkmcnt(4)
	v_mfma_f32_32x32x16_bf16 v[64:79], v[200:203], v[120:123], v[64:79]
	ds_read_b128 v[196:199], v221 offset:21536
	s_waitcnt lgkmcnt(4)
	v_mfma_f32_32x32x16_bf16 v[64:79], v[204:207], v[124:127], v[64:79]
	ds_read_b128 v[200:203], v221 offset:26112
	s_waitcnt lgkmcnt(4)
	v_mfma_f32_32x32x16_bf16 v[64:79], v[208:211], v[128:131], v[64:79]
	ds_read_b128 v[204:207], v221 offset:26144
	s_waitcnt lgkmcnt(4)
; __device__ __forceinline__ void attn_unit(KParams& P, int l, const AUnit& U, LAS unsigned char* lds) {
;     ...
;         if ((t + 1) * 64 > U.kvlen) {
;             const int kb0 = t * 64 + 8 * hi;
; #pragma unroll
;             for (int r = 0; r < 16; ++r) { const int kv = kb0 + 16 * (r >> 3) + (r & 7); if (kv >= U.kvlen) p0[r] = -INFINITY; if (kv + 32 >= U.kvlen) p1[r] = -INFINITY; }
;         }
;         float mx = fmaxf(p0[0], p1[0]);
; #pragma unroll
;         for (int r = 1; r < 16; ++r) mx = fmaxf(mx, fmaxf(p0[r], p1[r]));
;         { const auto rr = __builtin_amdgcn_permlane32_swap(__float_as_uint(mx), __float_as_uint(mx), false, false);
;           mx = fmaxf(__uint_as_float(rr[0]), __uint_as_float(rr[1])); }
;         const float mnew = fmaxf(mrun, mx); const float f = __builtin_amdgcn_exp2f(mrun - mnew); const bool grew = __any(mnew > mrun); mrun = mnew;
;         f32x2 ps2 = {0.f, 0.f}; const f32x2 nm2 = {-mnew, -mnew};
; #pragma unroll
;         for (int r = 0; r < 16; r += 2) { f32x2 a = (f32x2){p0[r], p0[r + 1]} + nm2, b = (f32x2){p1[r], p1[r + 1]} + nm2;
;             a[0] = __builtin_amdgcn_exp2f(a[0]); a[1] = __builtin_amdgcn_exp2f(a[1]); b[0] = __builtin_amdgcn_exp2f(b[0]); b[1] = __builtin_amdgcn_exp2f(b[1]);
;             p0[r] = a[0]; p0[r + 1] = a[1]; p1[r] = b[0]; p1[r + 1] = b[1]; ps2 += a; ps2 += b; }
;         const float ps = ps2[0] + ps2[1];
;         lrun = lrun * f + ps;
;         if (grew) {
; #pragma unroll
;             for (int d = 0; d < 4; ++d)
; #pragma unroll
;                 for (int r = 0; r < 16; ++r) o[d][r] *= f;
;         }
;         bf16x8 pf[4];
;         { u32x4 w;
;           w.x = cvt_pk_bf16(p0[0], p0[1]); w.y = cvt_pk_bf16(p0[2], p0[3]); w.z = cvt_pk_bf16(p0[4], p0[5]); w.w = cvt_pk_bf16(p0[6], p0[7]); pf[0] = __builtin_bit_cast(bf16x8, w);
;           w.x = cvt_pk_bf16(p0[8], p0[9]); w.y = cvt_pk_bf16(p0[10], p0[11]); w.z = cvt_pk_bf16(p0[12], p0[13]); w.w = cvt_pk_bf16(p0[14], p0[15]); pf[1] = __builtin_bit_cast(bf16x8, w);
;           w.x = cvt_pk_bf16(p1[0], p1[1]); w.y = cvt_pk_bf16(p1[2], p1[3]); w.z = cvt_pk_bf16(p1[4], p1[5]); w.w = cvt_pk_bf16(p1[6], p1[7]); pf[2] = __builtin_bit_cast(bf16x8, w);
;           w.x = cvt_pk_bf16(p1[8], p1[9]); w.y = cvt_pk_bf16(p1[10], p1[11]); w.z = cvt_pk_bf16(p1[12], p1[13]); w.w = cvt_pk_bf16(p1[14], p1[15]); pf[3] = __builtin_bit_cast(bf16x8, w); }
	v_mfma_f32_32x32x16_bf16 v[64:79], v[226:229], v[132:135], v[64:79]
	ds_read_b128 v[208:211], v221 offset:30720
	s_nop 15
	s_nop 3
	v_max_f32_e32 v180, 0, v180
	v_exp_f32_e64 v182, -v180
	s_nop 0
	v_pk_mul_f32 v[62:63], v[62:63], v[182:183] op_sel_hi:[1,0]
	v_pk_mul_f32 v[60:61], v[60:61], v[182:183] op_sel_hi:[1,0]
	v_pk_mul_f32 v[58:59], v[58:59], v[182:183] op_sel_hi:[1,0]
	v_pk_mul_f32 v[56:57], v[56:57], v[182:183] op_sel_hi:[1,0]
	v_pk_mul_f32 v[54:55], v[54:55], v[182:183] op_sel_hi:[1,0]
	v_pk_mul_f32 v[52:53], v[52:53], v[182:183] op_sel_hi:[1,0]
	v_pk_mul_f32 v[50:51], v[50:51], v[182:183] op_sel_hi:[1,0]
	v_pk_mul_f32 v[48:49], v[48:49], v[182:183] op_sel_hi:[1,0]
	v_pk_mul_f32 v[46:47], v[46:47], v[182:183] op_sel_hi:[1,0]
	v_pk_mul_f32 v[44:45], v[44:45], v[182:183] op_sel_hi:[1,0]
	v_pk_mul_f32 v[42:43], v[42:43], v[182:183] op_sel_hi:[1,0]
	v_pk_mul_f32 v[40:41], v[40:41], v[182:183] op_sel_hi:[1,0]
	v_pk_mul_f32 v[38:39], v[38:39], v[182:183] op_sel_hi:[1,0]
	v_pk_mul_f32 v[36:37], v[36:37], v[182:183] op_sel_hi:[1,0]
	v_pk_mul_f32 v[34:35], v[34:35], v[182:183] op_sel_hi:[1,0]
	v_pk_mul_f32 v[32:33], v[32:33], v[182:183] op_sel_hi:[1,0]
	v_pk_mul_f32 v[30:31], v[30:31], v[182:183] op_sel_hi:[1,0]
	v_pk_mul_f32 v[28:29], v[28:29], v[182:183] op_sel_hi:[1,0]
	v_pk_mul_f32 v[26:27], v[26:27], v[182:183] op_sel_hi:[1,0]
	v_pk_mul_f32 v[24:25], v[24:25], v[182:183] op_sel_hi:[1,0]
	v_pk_mul_f32 v[22:23], v[22:23], v[182:183] op_sel_hi:[1,0]
	v_pk_mul_f32 v[20:21], v[20:21], v[182:183] op_sel_hi:[1,0]
	v_pk_mul_f32 v[18:19], v[18:19], v[182:183] op_sel_hi:[1,0]
	v_pk_mul_f32 v[16:17], v[16:17], v[182:183] op_sel_hi:[1,0]
	v_pk_mul_f32 v[14:15], v[14:15], v[182:183] op_sel_hi:[1,0]
	v_pk_mul_f32 v[12:13], v[12:13], v[182:183] op_sel_hi:[1,0]
	v_pk_mul_f32 v[10:11], v[10:11], v[182:183] op_sel_hi:[1,0]
	v_pk_mul_f32 v[8:9], v[8:9], v[182:183] op_sel_hi:[1,0]
	v_pk_mul_f32 v[6:7], v[6:7], v[182:183] op_sel_hi:[1,0]
	v_pk_mul_f32 v[4:5], v[4:5], v[182:183] op_sel_hi:[1,0]
	v_pk_mul_f32 v[2:3], v[2:3], v[182:183] op_sel_hi:[1,0]
	v_pk_mul_f32 v[0:1], v[0:1], v[182:183] op_sel_hi:[1,0]
	v_mul_f32_e32 v167, v167, v182
	v_sub_f32_e32 v80, v80, v180
	v_sub_f32_e32 v81, v81, v180
	v_sub_f32_e32 v82, v82, v180
	v_sub_f32_e32 v83, v83, v180
	v_sub_f32_e32 v84, v84, v180
	v_sub_f32_e32 v85, v85, v180
	v_sub_f32_e32 v86, v86, v180
	v_sub_f32_e32 v87, v87, v180
	v_sub_f32_e32 v88, v88, v180
	v_sub_f32_e32 v89, v89, v180
	v_sub_f32_e32 v90, v90, v180
	v_sub_f32_e32 v91, v91, v180
	v_sub_f32_e32 v92, v92, v180
	v_sub_f32_e32 v93, v93, v180
	v_sub_f32_e32 v94, v94, v180
	v_sub_f32_e32 v95, v95, v180
	v_add_f32_e32 v169, v169, v180
	v_exp_f32_e32 v80, v80
	v_exp_f32_e32 v81, v81
	v_exp_f32_e32 v82, v82
	v_exp_f32_e32 v83, v83
	v_exp_f32_e32 v84, v84
	v_exp_f32_e32 v85, v85
	v_exp_f32_e32 v86, v86
	v_exp_f32_e32 v87, v87
	v_exp_f32_e32 v88, v88
	v_exp_f32_e32 v89, v89
	v_exp_f32_e32 v90, v90
	v_exp_f32_e32 v91, v91
	v_exp_f32_e32 v92, v92
	v_exp_f32_e32 v93, v93
	v_exp_f32_e32 v94, v94
	v_exp_f32_e32 v95, v95
	v_add_f32_e32 v252, v80, v81
	v_add_f32_e32 v253, v88, v89
	v_add_f32_e32 v252, v252, v82
	v_add_f32_e32 v253, v253, v90
	v_add_f32_e32 v252, v252, v83
	v_add_f32_e32 v253, v253, v91
	v_add_f32_e32 v252, v252, v84
	v_add_f32_e32 v253, v253, v92
	v_add_f32_e32 v252, v252, v85
	v_add_f32_e32 v253, v253, v93
	v_add_f32_e32 v252, v252, v86
	v_add_f32_e32 v253, v253, v94
	v_add_f32_e32 v252, v252, v87
	v_add_f32_e32 v253, v253, v95
	v_add_f32_e32 v252, v252, v253
	v_add_f32_e32 v167, v167, v252
	v_cvt_pk_bf16_f32 v80, v80, v81
	v_cvt_pk_bf16_f32 v81, v82, v83
	v_cvt_pk_bf16_f32 v82, v84, v85
	v_cvt_pk_bf16_f32 v83, v86, v87
	v_cvt_pk_bf16_f32 v84, v88, v89
	v_cvt_pk_bf16_f32 v85, v90, v91
	v_cvt_pk_bf16_f32 v86, v92, v93
	v_cvt_pk_bf16_f32 v87, v94, v95
	s_branch .Lp_end
.Lp_maskmid:
	v_add_u32_e32 v252, s25, v164
	v_add_u32_e32 v253, 0, v252
	v_cmp_gt_u32_e32 vcc, s70, v253
	s_nop 1
	v_cndmask_b32_e32 v80, v225, v80, vcc
	v_add_u32_e32 v253, 1, v252
	v_cmp_gt_u32_e32 vcc, s70, v253
	s_nop 1
	v_cndmask_b32_e32 v81, v225, v81, vcc
	v_add_u32_e32 v253, 2, v252
	v_cmp_gt_u32_e32 vcc, s70, v253
	s_nop 1
	v_cndmask_b32_e32 v82, v225, v82, vcc
	v_add_u32_e32 v253, 3, v252
	v_cmp_gt_u32_e32 vcc, s70, v253
	s_nop 1
	v_cndmask_b32_e32 v83, v225, v83, vcc
	v_add_u32_e32 v253, 4, v252
	v_cmp_gt_u32_e32 vcc, s70, v253
	s_nop 1
	v_cndmask_b32_e32 v84, v225, v84, vcc
	v_add_u32_e32 v253, 5, v252
	v_cmp_gt_u32_e32 vcc, s70, v253
	s_nop 1
	v_cndmask_b32_e32 v85, v225, v85, vcc
	v_add_u32_e32 v253, 6, v252
	v_cmp_gt_u32_e32 vcc, s70, v253
	s_nop 1
	v_cndmask_b32_e32 v86, v225, v86, vcc
	v_add_u32_e32 v253, 7, v252
	v_cmp_gt_u32_e32 vcc, s70, v253
	s_nop 1
	v_cndmask_b32_e32 v87, v225, v87, vcc
	v_add_u32_e32 v253, 16, v252
	v_cmp_gt_u32_e32 vcc, s70, v253
	s_nop 1
	v_cndmask_b32_e32 v88, v225, v88, vcc
	v_add_u32_e32 v253, 17, v252
	v_cmp_gt_u32_e32 vcc, s70, v253
	s_nop 1
	v_cndmask_b32_e32 v89, v225, v89, vcc
	v_add_u32_e32 v253, 18, v252
	v_cmp_gt_u32_e32 vcc, s70, v253
	s_nop 1
	v_cndmask_b32_e32 v90, v225, v90, vcc
	v_add_u32_e32 v253, 19, v252
	v_cmp_gt_u32_e32 vcc, s70, v253
	s_nop 1
	v_cndmask_b32_e32 v91, v225, v91, vcc
	v_add_u32_e32 v253, 20, v252
	v_cmp_gt_u32_e32 vcc, s70, v253
	s_nop 1
	v_cndmask_b32_e32 v92, v225, v92, vcc
	v_add_u32_e32 v253, 21, v252
	v_cmp_gt_u32_e32 vcc, s70, v253
	s_nop 1
	v_cndmask_b32_e32 v93, v225, v93, vcc
	v_add_u32_e32 v253, 22, v252
	v_cmp_gt_u32_e32 vcc, s70, v253
	s_nop 1
	v_cndmask_b32_e32 v94, v225, v94, vcc
	v_add_u32_e32 v253, 23, v252
	v_cmp_gt_u32_e32 vcc, s70, v253
	s_nop 1
	v_cndmask_b32_e32 v95, v225, v95, vcc
	s_branch .Lp_maskmid_ret
